# SG in-proj gv-tile epilogue: removed 8 redundant vmcnt(0) waits before the row-stat stores (they waited on store acks and the next unit's in-flight LDS-DMA)
# speedup vs baseline: 1.0088x; 1.0088x over previous
; __device__ __forceinline__ float gelu_f(float x) { const float u = 0.7978845608028654f * (x + 0.044715f * x * x * x); return x * frcp(1.f + fexp2(-2.885390081777927f * u)); }
; __device__ __forceinline__ void st8(bf16_t* p, const float (&v)[8]) { u32x4 w; w.x = pk2(v[0], v[1]); w.y = pk2(v[2], v[3]); w.z = pk2(v[4], v[5]); w.w = pk2(v[6], v[7]); *(u32x4*)p = w; }
;     __device__ __forceinline__ void operator()(const f32x4 (&acc)[2][2][4][2], const Unit& u, int wr, int wc, int fr, int fq) const {
;     ...
;             const int colt = (pn - 16) * 256 + wc * 32 + 8 * fq;
; #pragma unroll
;             for (int ai = 0; ai < 2; ++ai)
; #pragma unroll
;                 for (int m = 0; m < 4; ++m) { const int row = row0 + ai * 128 + m * 16; float s1 = 0.f, s2 = 0.f;
; #pragma unroll
;                     for (int bj = 0; bj < 2; ++bj) { float o[8];
; #pragma unroll
;                         for (int j = 0; j < 4; ++j) { o[j] = gelu_f(acc[ai][bj][m][0][j]); o[4 + j] = gelu_f(acc[ai][bj][m][1][j]); }
; #pragma unroll
;                         for (int j = 0; j < 8; ++j) { s1 += o[j]; s2 += o[j] * o[j]; }
;                         st8(gv + (size_t)row * DM + colt + bj * 128, o); }
;                     s1 += __shfl_xor(s1, 16); s2 += __shfl_xor(s2, 16); s1 += __shfl_xor(s1, 32); s2 += __shfl_xor(s2, 32);
;                     if (fq == 0) { float2 w; w.x = s1; w.y = s2; *(float2*)(stats + ((size_t)row * 32 + (pn - 16) * 4 + wc) * 2) = w; }
.LBB0_312:
	v_lshl_add_u32 v142, s4, 8, v150
	v_mul_f32_e32 v0, 0x3d372713, v126
	v_mul_f32_e32 v144, 0x3d372713, v122
	v_mul_f32_e32 v145, 0x3d372713, v127
	v_mul_f32_e32 v146, 0x3d372713, v123
	v_mul_f32_e32 v147, 0x3d372713, v128
	v_mul_f32_e32 v148, 0x3d372713, v124
	v_mul_f32_e32 v149, 0x3d372713, v129
	v_mul_f32_e32 v154, 0x3d372713, v125
	s_mov_b64 s[12:13], -1
	s_cmp_gt_i32 s89, 15
	v_ashrrev_i32_e32 v143, 31, v142
	v_mul_f32_e32 v161, v126, v0
	v_mul_f32_e32 v160, v122, v144
	v_mul_f32_e32 v159, v127, v145
	v_mul_f32_e32 v158, v123, v146
	v_mul_f32_e32 v157, v128, v147
	v_mul_f32_e32 v156, v124, v148
	v_mul_f32_e32 v155, v129, v149
	v_mul_f32_e32 v154, v125, v154
	s_cbranch_scc0 .LBB0_331
	v_fma_f32 v147, v127, v159, v127
	v_mul_f32_e32 v147, 0x3f4c422a, v147
	v_mul_f32_e32 v147, 0xc038aa3b, v147
	v_exp_f32_e32 v147, v147
	v_fma_f32 v146, v126, v161, v126
	v_mul_f32_e32 v146, 0x3f4c422a, v146
	v_mul_f32_e32 v146, 0xc038aa3b, v146
	v_add_f32_e32 v147, 1.0, v147
	v_rcp_f32_e32 v164, v147
	v_fma_f32 v147, v123, v158, v123
	v_mul_f32_e32 v147, 0x3f4c422a, v147
	v_mul_f32_e32 v147, 0xc038aa3b, v147
	v_exp_f32_e32 v147, v147
	v_exp_f32_e32 v146, v146
	v_mul_f32_e32 v167, v127, v164
	v_mul_f32_e32 v169, v167, v167
	v_add_f32_e32 v147, 1.0, v147
	v_rcp_f32_e32 v148, v147
	v_fma_f32 v147, v128, v157, v128
	v_mul_f32_e32 v147, 0x3f4c422a, v147
	v_mul_f32_e32 v147, 0xc038aa3b, v147
	v_exp_f32_e32 v147, v147
	v_add_f32_e32 v146, 1.0, v146
	v_rcp_f32_e32 v163, v146
	v_fma_f32 v146, v122, v160, v122
	v_add_f32_e32 v147, 1.0, v147
	v_rcp_f32_e32 v165, v147
	v_fma_f32 v147, v124, v156, v124
	v_mul_f32_e32 v147, 0x3f4c422a, v147
	v_mul_f32_e32 v147, 0xc038aa3b, v147
	v_exp_f32_e32 v147, v147
	v_mul_f32_e32 v146, 0x3f4c422a, v146
	v_mul_f32_e32 v146, 0xc038aa3b, v146
	v_exp_f32_e32 v146, v146
	v_add_f32_e32 v147, 1.0, v147
	v_rcp_f32_e32 v149, v147
	v_fma_f32 v147, v129, v155, v129
	v_mul_f32_e32 v147, 0x3f4c422a, v147
	v_mul_f32_e32 v147, 0xc038aa3b, v147
	v_exp_f32_e32 v147, v147
	v_add_f32_e32 v146, 1.0, v146
	v_rcp_f32_e32 v146, v146
	v_mul_f32_e32 v166, v126, v163
	v_add_f32_e32 v147, 1.0, v147
	v_rcp_f32_e32 v147, v147
	v_fma_f32 v163, v126, v163, 0
	v_fmac_f32_e32 v163, v127, v164
	v_mul_f32_e32 v168, v128, v165
	v_fmac_f32_e32 v163, v128, v165
	v_mov_b32_e32 v164, v122
	v_mov_b32_e32 v165, v129
	v_fmac_f32_e32 v169, v166, v166
	v_pk_mul_f32 v[164:165], v[164:165], v[146:147]
	v_fmac_f32_e32 v169, v168, v168
	v_pk_mul_f32 v[146:147], v[164:165], v[164:165]
	v_add_f32_e32 v163, v165, v163
	v_add_f32_e32 v147, v147, v169
	v_add_f32_e32 v169, v146, v147
	v_mov_b32_e32 v146, v123
	v_mov_b32_e32 v147, v124
	v_pk_mul_f32 v[148:149], v[146:147], v[148:149]
	v_add_f32_e32 v163, v164, v163
	v_pk_mul_f32 v[146:147], v[148:149], v[148:149]
	v_add_f32_e32 v163, v148, v163
	v_add_f32_e32 v146, v146, v169
	v_add_f32_e32 v175, v147, v146
	v_cvt_pk_bf16_f32 v147, v168, v165
	v_mul_f32_e32 v165, 0x3d372713, v119
	v_mul_f32_e32 v165, v119, v165
	v_fma_f32 v165, v119, v165, v119
	v_mul_f32_e32 v165, 0x3f4c422a, v165
	v_mul_f32_e32 v165, 0xc038aa3b, v165
	v_exp_f32_e32 v165, v165
	v_cvt_pk_bf16_f32 v146, v166, v167
	v_add_f32_e32 v174, v149, v163
	v_mul_f32_e32 v163, 0x3d372713, v118
	v_add_f32_e32 v165, 1.0, v165
	v_rcp_f32_e32 v166, v165
	v_mul_f32_e32 v165, 0x3d372713, v115
	v_mul_f32_e32 v165, v115, v165
	v_fma_f32 v165, v115, v165, v115
	v_mul_f32_e32 v165, 0x3f4c422a, v165
	v_mul_f32_e32 v165, 0xc038aa3b, v165
	v_exp_f32_e32 v165, v165
	v_mul_f32_e32 v163, v118, v163
	v_fma_f32 v162, v125, v154, v125
	v_fma_f32 v163, v118, v163, v118
	v_add_f32_e32 v165, 1.0, v165
	v_rcp_f32_e32 v168, v165
	v_mul_f32_e32 v165, 0x3d372713, v120
	v_mul_f32_e32 v165, v120, v165
	v_fma_f32 v165, v120, v165, v120
	v_mul_f32_e32 v165, 0x3f4c422a, v165
	v_mul_f32_e32 v165, 0xc038aa3b, v165
	v_exp_f32_e32 v165, v165
	v_mul_f32_e32 v162, 0x3f4c422a, v162
	v_mul_f32_e32 v163, 0x3f4c422a, v163
	v_mul_f32_e32 v162, 0xc038aa3b, v162
	v_add_f32_e32 v165, 1.0, v165
	v_rcp_f32_e32 v167, v165
	v_mul_f32_e32 v165, 0x3d372713, v116
	v_mul_f32_e32 v165, v116, v165
	v_fma_f32 v165, v116, v165, v116
	v_mul_f32_e32 v165, 0x3f4c422a, v165
	v_mul_f32_e32 v165, 0xc038aa3b, v165
	v_exp_f32_e32 v165, v165
	v_mul_f32_e32 v163, 0xc038aa3b, v163
	v_exp_f32_e32 v162, v162
	v_exp_f32_e32 v163, v163
	v_add_f32_e32 v165, 1.0, v165
	v_cvt_pk_bf16_f32 v148, v164, v148
	v_mul_f32_e32 v164, 0x3d372713, v114
	v_rcp_f32_e32 v170, v165
	v_mul_f32_e32 v165, 0x3d372713, v121
	v_mul_f32_e32 v164, v114, v164
	v_mul_f32_e32 v165, v121, v165
	v_fma_f32 v164, v114, v164, v114
	v_fma_f32 v165, v121, v165, v121
	v_add_f32_e32 v162, 1.0, v162
	v_add_f32_e32 v163, 1.0, v163
	v_mul_f32_e32 v164, 0x3f4c422a, v164
	v_mul_f32_e32 v165, 0x3f4c422a, v165
	v_mul_f32_e32 v171, 0x3d372713, v117
	v_rcp_f32_e32 v162, v162
	v_rcp_f32_e32 v163, v163
	v_mul_f32_e32 v164, 0xc038aa3b, v164
	v_mul_f32_e32 v165, 0xc038aa3b, v165
	v_mul_f32_e32 v171, v117, v171
	s_add_i32 s2, s89, -16
	v_exp_f32_e32 v164, v164
	v_exp_f32_e32 v165, v165
	v_fma_f32 v171, v117, v171, v117
	v_lshl_or_b32 v0, s2, 8, v152
	v_lshlrev_b64 v[144:145], 12, v[142:143]
	v_mul_f32_e32 v171, 0x3f4c422a, v171
	v_lshl_add_u64 v[144:145], s[46:47], 0, v[144:145]
	v_lshlrev_b32_e32 v0, 1, v0
	v_mul_f32_e32 v171, 0xc038aa3b, v171
	v_pk_mov_b32 v[172:173], v[124:125], v[118:119] op_sel:[1,0]
	v_lshl_add_u64 v[144:145], v[144:145], 0, v[0:1]
	v_exp_f32_e32 v171, v171
	v_pk_mul_f32 v[162:163], v[172:173], v[162:163]
	v_add_f32_e32 v164, 1.0, v164
	v_add_f32_e32 v165, 1.0, v165
	v_add_f32_e32 v174, v162, v174
	v_pk_mul_f32 v[172:173], v[162:163], v[162:163]
	v_cvt_pk_bf16_f32 v149, v149, v162
; __device__ __forceinline__ float gelu_f(float x) { const float u = 0.7978845608028654f * (x + 0.044715f * x * x * x); return x * frcp(1.f + fexp2(-2.885390081777927f * u)); }
; __device__ __forceinline__ void st8(bf16_t* p, const float (&v)[8]) { u32x4 w; w.x = pk2(v[0], v[1]); w.y = pk2(v[2], v[3]); w.z = pk2(v[4], v[5]); w.w = pk2(v[6], v[7]); *(u32x4*)p = w; }
;     __device__ __forceinline__ void operator()(const f32x4 (&acc)[2][2][4][2], const Unit& u, int wr, int wc, int fr, int fq) const {
;     ...
;                     for (int bj = 0; bj < 2; ++bj) { float o[8];
; #pragma unroll
;                         for (int j = 0; j < 4; ++j) { o[j] = gelu_f(acc[ai][bj][m][0][j]); o[4 + j] = gelu_f(acc[ai][bj][m][1][j]); }
; #pragma unroll
;                         for (int j = 0; j < 8; ++j) { s1 += o[j]; s2 += o[j] * o[j]; }
;                         st8(gv + (size_t)row * DM + colt + bj * 128, o); }
;                     s1 += __shfl_xor(s1, 16); s2 += __shfl_xor(s2, 16); s1 += __shfl_xor(s1, 32); s2 += __shfl_xor(s2, 32);
;                     if (fq == 0) { float2 w; w.x = s1; w.y = s2; *(float2*)(stats + ((size_t)row * 32 + (pn - 16) * 4 + wc) * 2) = w; }
	global_store_dwordx4 v[144:145], v[146:149], off
	v_rcp_f32_e32 v164, v164
	v_rcp_f32_e32 v165, v165
	v_mov_b32_e32 v146, v119
	v_mov_b32_e32 v147, v120
	v_add_f32_e32 v172, v172, v175
	v_add_f32_e32 v148, v174, v163
	v_pk_mul_f32 v[146:147], v[146:147], v[166:167]
	v_add_f32_e32 v162, v172, v173
	v_add_f32_e32 v166, v146, v148
	v_pk_mul_f32 v[148:149], v[146:147], v[146:147]
	v_add_f32_e32 v171, 1.0, v171
	v_add_f32_e32 v148, v148, v162
	v_rcp_f32_e32 v171, v171
	v_add_f32_e32 v162, v147, v166
	v_add_f32_e32 v166, v149, v148
	v_mov_b32_e32 v148, v114
	v_mov_b32_e32 v149, v121
	v_pk_mul_f32 v[148:149], v[148:149], v[164:165]
	v_mul_f32_e32 v169, v115, v168
	v_pk_mul_f32 v[164:165], v[148:149], v[148:149]
	v_add_f32_e32 v162, v149, v162
	v_add_f32_e32 v165, v165, v166
	v_add_f32_e32 v162, v148, v162
	v_add_f32_e32 v172, v164, v165
	v_pk_mul_f32 v[164:165], v[116:117], v[170:171]
	v_fmac_f32_e32 v162, v115, v168
	v_mov_b32_e32 v168, v164
	v_pk_mul_f32 v[166:167], v[168:169], v[168:169]
	v_cvt_pk_bf16_f32 v147, v147, v149
	v_cvt_pk_bf16_f32 v146, v163, v146
	v_cvt_pk_bf16_f32 v148, v148, v169
	v_mov_b32_e32 v163, v165
	v_add_f32_e32 v149, v167, v172
	v_add_f32_e32 v167, v166, v149
	v_cvt_pk_bf16_f32 v149, v164, v165
	global_store_dwordx4 v[144:145], v[146:149], off offset:256
	v_and_b32_e32 v145, 64, v182
	v_xor_b32_e32 v144, 16, v182
	v_add_u32_e32 v146, 64, v145
	v_pk_fma_f32 v[162:163], v[116:117], v[170:171], v[162:163]
	v_pk_mul_f32 v[168:169], v[164:165], v[164:165]
	v_cmp_lt_i32_e32 vcc, v144, v146
	v_mov_b32_e32 v163, v169
	v_mov_b32_e32 v166, v165
	v_cndmask_b32_e32 v144, v182, v144, vcc
	v_pk_add_f32 v[166:167], v[162:163], v[166:167]
	v_lshlrev_b32_e32 v162, 2, v144
	ds_bpermute_b32 v144, v162, v166
	ds_bpermute_b32 v145, v162, v167
	v_xor_b32_e32 v147, 32, v182
	v_cmp_lt_i32_e32 vcc, v147, v146
	s_lshl_b32 s2, s2, 2
	s_or_b32 s30, s2, s73
	v_cndmask_b32_e32 v146, v182, v147, vcc
	s_waitcnt lgkmcnt(0)
	v_pk_add_f32 v[144:145], v[166:167], v[144:145]
	v_lshlrev_b32_e32 v163, 2, v146
	ds_bpermute_b32 v146, v163, v144
	ds_bpermute_b32 v147, v163, v145
	s_and_saveexec_b64 s[12:13], s[40:41]
	s_cbranch_execz .LBB0_315
	v_lshlrev_b64 v[148:149], 8, v[142:143]
	v_lshl_add_u64 v[148:149], s[48:49], 0, v[148:149]
	v_lshl_add_u64 v[148:149], s[30:31], 3, v[148:149]
	s_waitcnt lgkmcnt(0)
	v_pk_add_f32 v[144:145], v[144:145], v[146:147]
	global_store_dwordx2 v[148:149], v[144:145], off
.LBB0_315:
	s_or_b64 exec, exec, s[12:13]
	v_mul_f32_e32 v149, 0x3d372713, v111
	v_mul_f32_e32 v149, v111, v149
	v_fma_f32 v149, v111, v149, v111
	v_mul_f32_e32 v149, 0x3f4c422a, v149
	v_mul_f32_e32 v149, 0xc038aa3b, v149
	v_exp_f32_e32 v149, v149
	v_mul_f32_e32 v148, 0x3d372713, v110
	v_mul_f32_e32 v148, v110, v148
	v_fma_f32 v148, v110, v148, v110
	v_add_f32_e32 v149, 1.0, v149
	v_rcp_f32_e32 v167, v149
	v_mul_f32_e32 v149, 0x3d372713, v107
	v_mul_f32_e32 v149, v107, v149
	v_fma_f32 v149, v107, v149, v107
	v_mul_f32_e32 v149, 0x3f4c422a, v149
	v_mul_f32_e32 v149, 0xc038aa3b, v149
	v_exp_f32_e32 v149, v149
	v_mul_f32_e32 v148, 0x3f4c422a, v148
	v_mul_f32_e32 v148, 0xc038aa3b, v148
	v_exp_f32_e32 v148, v148
	v_add_f32_e32 v149, 1.0, v149
	v_rcp_f32_e32 v164, v149
	v_mul_f32_e32 v149, 0x3d372713, v112
	v_mul_f32_e32 v149, v112, v149
	v_fma_f32 v149, v112, v149, v112
	v_mul_f32_e32 v149, 0x3f4c422a, v149
	v_mul_f32_e32 v149, 0xc038aa3b, v149
	v_exp_f32_e32 v149, v149
	v_add_f32_e32 v148, 1.0, v148
	v_rcp_f32_e32 v166, v148
	v_mul_f32_e32 v148, 0x3d372713, v106
	v_add_f32_e32 v149, 1.0, v149
	v_rcp_f32_e32 v171, v149
	v_mul_f32_e32 v149, 0x3d372713, v108
	v_mul_f32_e32 v149, v108, v149
	v_fma_f32 v149, v108, v149, v108
	v_mul_f32_e32 v149, 0x3f4c422a, v149
	v_mul_f32_e32 v149, 0xc038aa3b, v149
	v_exp_f32_e32 v149, v149
	v_mul_f32_e32 v148, v106, v148
	v_fma_f32 v148, v106, v148, v106
	v_mul_f32_e32 v148, 0x3f4c422a, v148
	v_add_f32_e32 v149, 1.0, v149
	v_rcp_f32_e32 v165, v149
	v_mul_f32_e32 v149, 0x3d372713, v113
	v_mul_f32_e32 v149, v113, v149
	v_fma_f32 v149, v113, v149, v113
	v_mul_f32_e32 v149, 0x3f4c422a, v149
	v_mul_f32_e32 v148, 0xc038aa3b, v148
	v_mul_f32_e32 v149, 0xc038aa3b, v149
	v_exp_f32_e32 v148, v148
	v_exp_f32_e32 v149, v149
	v_mul_f32_e32 v170, v111, v167
	v_fma_f32 v173, v110, v166, 0
	v_add_f32_e32 v148, 1.0, v148
	v_add_f32_e32 v149, 1.0, v149
	v_rcp_f32_e32 v148, v148
	v_rcp_f32_e32 v149, v149
	v_mul_f32_e32 v169, v110, v166
	v_fmac_f32_e32 v173, v111, v167
	v_mul_f32_e32 v174, v170, v170
	v_mov_b32_e32 v166, v106
	v_mov_b32_e32 v167, v113
	v_mul_f32_e32 v172, v112, v171
	v_fmac_f32_e32 v174, v169, v169
	v_pk_mul_f32 v[148:149], v[166:167], v[148:149]
	v_fmac_f32_e32 v174, v172, v172
	v_pk_mul_f32 v[166:167], v[148:149], v[148:149]
	v_fmac_f32_e32 v173, v112, v171
	v_add_f32_e32 v167, v167, v174
	v_add_f32_e32 v171, v149, v173
	v_add_f32_e32 v173, v166, v167
	v_mov_b32_e32 v166, v107
	v_mov_b32_e32 v167, v108
	v_pk_mul_f32 v[166:167], v[166:167], v[164:165]
	v_add_f32_e32 v171, v148, v171
	v_pk_mul_f32 v[164:165], v[166:167], v[166:167]
	v_add_f32_e32 v171, v166, v171
	v_add_f32_e32 v164, v164, v173
	v_add_f32_e32 v186, v165, v164
	v_cvt_pk_bf16_f32 v165, v172, v149
	v_mul_f32_e32 v149, 0x3d372713, v103
	v_mul_f32_e32 v149, v103, v149
	v_fma_f32 v149, v103, v149, v103
	v_mul_f32_e32 v149, 0x3f4c422a, v149
	v_mul_f32_e32 v149, 0xc038aa3b, v149
	v_exp_f32_e32 v149, v149
	v_cvt_pk_bf16_f32 v164, v169, v170
	v_add_f32_e32 v185, v167, v171
	v_cvt_pk_bf16_f32 v166, v148, v166
	v_add_f32_e32 v149, 1.0, v149
	v_rcp_f32_e32 v170, v149
	v_mul_f32_e32 v149, 0x3d372713, v99
	v_mul_f32_e32 v149, v99, v149
	v_fma_f32 v149, v99, v149, v99
; __device__ __forceinline__ float gelu_f(float x) { const float u = 0.7978845608028654f * (x + 0.044715f * x * x * x); return x * frcp(1.f + fexp2(-2.885390081777927f * u)); }
; __device__ __forceinline__ void st8(bf16_t* p, const float (&v)[8]) { u32x4 w; w.x = pk2(v[0], v[1]); w.y = pk2(v[2], v[3]); w.z = pk2(v[4], v[5]); w.w = pk2(v[6], v[7]); *(u32x4*)p = w; }
;     __device__ __forceinline__ void operator()(const f32x4 (&acc)[2][2][4][2], const Unit& u, int wr, int wc, int fr, int fq) const {
;     ...
;                     for (int bj = 0; bj < 2; ++bj) { float o[8];
; #pragma unroll
;                         for (int j = 0; j < 4; ++j) { o[j] = gelu_f(acc[ai][bj][m][0][j]); o[4 + j] = gelu_f(acc[ai][bj][m][1][j]); }
; #pragma unroll
;                         for (int j = 0; j < 8; ++j) { s1 += o[j]; s2 += o[j] * o[j]; }
;                         st8(gv + (size_t)row * DM + colt + bj * 128, o); }
;                     s1 += __shfl_xor(s1, 16); s2 += __shfl_xor(s2, 16); s1 += __shfl_xor(s1, 32); s2 += __shfl_xor(s2, 32);
;                     if (fq == 0) { float2 w; w.x = s1; w.y = s2; *(float2*)(stats + ((size_t)row * 32 + (pn - 16) * 4 + wc) * 2) = w; }
	v_mul_f32_e32 v149, 0x3f4c422a, v149
	v_mul_f32_e32 v149, 0xc038aa3b, v149
	v_exp_f32_e32 v149, v149
	v_mul_f32_e32 v148, 0x3d372713, v102
	v_mul_f32_e32 v148, v102, v148
	v_fma_f32 v148, v102, v148, v102
	v_add_f32_e32 v149, 1.0, v149
	v_rcp_f32_e32 v172, v149
	v_mul_f32_e32 v149, 0x3d372713, v104
	v_mul_f32_e32 v149, v104, v149
	v_fma_f32 v149, v104, v149, v104
	v_mul_f32_e32 v149, 0x3f4c422a, v149
	v_mul_f32_e32 v149, 0xc038aa3b, v149
	v_exp_f32_e32 v149, v149
	v_mul_f32_e32 v148, 0x3f4c422a, v148
	v_mul_f32_e32 v168, 0x3d372713, v109
	v_mul_f32_e32 v148, 0xc038aa3b, v148
	v_add_f32_e32 v149, 1.0, v149
	v_rcp_f32_e32 v171, v149
	v_mul_f32_e32 v149, 0x3d372713, v100
	v_mul_f32_e32 v149, v100, v149
	v_fma_f32 v149, v100, v149, v100
	v_mul_f32_e32 v149, 0x3f4c422a, v149
	v_mul_f32_e32 v149, 0xc038aa3b, v149
	v_mul_f32_e32 v168, v109, v168
	v_exp_f32_e32 v148, v148
	v_exp_f32_e32 v149, v149
	v_fma_f32 v168, v109, v168, v109
	v_mul_f32_e32 v168, 0x3f4c422a, v168
	v_mul_f32_e32 v168, 0xc038aa3b, v168
	v_exp_f32_e32 v168, v168
	v_add_f32_e32 v148, 1.0, v148
	v_add_f32_e32 v149, 1.0, v149
	v_rcp_f32_e32 v169, v148
	v_mul_f32_e32 v148, 0x3d372713, v98
	v_rcp_f32_e32 v174, v149
	v_mul_f32_e32 v149, 0x3d372713, v105
	v_mul_f32_e32 v148, v98, v148
	v_mul_f32_e32 v149, v105, v149
	v_fma_f32 v148, v98, v148, v98
	v_fma_f32 v149, v105, v149, v105
	v_add_f32_e32 v168, 1.0, v168
	v_mul_f32_e32 v148, 0x3f4c422a, v148
	v_mul_f32_e32 v149, 0x3f4c422a, v149
	v_mul_f32_e32 v175, 0x3d372713, v101
	v_or_b32_e32 v144, 16, v142
	v_rcp_f32_e32 v168, v168
	v_mul_f32_e32 v148, 0xc038aa3b, v148
	v_mul_f32_e32 v149, 0xc038aa3b, v149
	v_mul_f32_e32 v175, v101, v175
	v_ashrrev_i32_e32 v145, 31, v144
	v_exp_f32_e32 v148, v148
	v_exp_f32_e32 v149, v149
	v_fma_f32 v175, v101, v175, v101
	s_waitcnt lgkmcnt(0)
	v_lshlrev_b64 v[146:147], 12, v[144:145]
	v_mul_f32_e32 v175, 0x3f4c422a, v175
	v_lshl_add_u64 v[146:147], s[46:47], 0, v[146:147]
	v_mul_f32_e32 v175, 0xc038aa3b, v175
	v_pk_mov_b32 v[176:177], v[108:109], v[102:103] op_sel:[1,0]
	v_lshl_add_u64 v[146:147], v[146:147], 0, v[0:1]
	v_exp_f32_e32 v175, v175
	v_pk_mul_f32 v[168:169], v[176:177], v[168:169]
	v_add_f32_e32 v148, 1.0, v148
	v_add_f32_e32 v149, 1.0, v149
	v_add_f32_e32 v185, v168, v185
	v_pk_mul_f32 v[176:177], v[168:169], v[168:169]
	v_cvt_pk_bf16_f32 v167, v167, v168
	global_store_dwordx4 v[146:147], v[164:167], off
	v_rcp_f32_e32 v148, v148
	v_rcp_f32_e32 v149, v149
	v_mov_b32_e32 v164, v103
	v_mov_b32_e32 v165, v104
	v_add_f32_e32 v176, v176, v186
	v_add_f32_e32 v166, v185, v169
	v_pk_mul_f32 v[164:165], v[164:165], v[170:171]
	v_add_f32_e32 v168, v176, v177
	v_add_f32_e32 v170, v164, v166
	v_pk_mul_f32 v[166:167], v[164:165], v[164:165]
	v_add_f32_e32 v175, 1.0, v175
	v_add_f32_e32 v166, v166, v168
	v_rcp_f32_e32 v175, v175
	v_add_f32_e32 v168, v165, v170
	v_add_f32_e32 v170, v167, v166
	v_mov_b32_e32 v166, v98
	v_mov_b32_e32 v167, v105
	v_pk_mul_f32 v[148:149], v[166:167], v[148:149]
	v_mul_f32_e32 v173, v99, v172
	v_pk_mul_f32 v[166:167], v[148:149], v[148:149]
	v_add_f32_e32 v168, v149, v168
	v_add_f32_e32 v167, v167, v170
	v_add_f32_e32 v168, v148, v168
	v_add_f32_e32 v167, v166, v167
	v_cvt_pk_bf16_f32 v165, v165, v149
	v_cvt_pk_bf16_f32 v166, v148, v173
	v_pk_mul_f32 v[148:149], v[100:101], v[174:175]
	v_fmac_f32_e32 v168, v99, v172
	v_mov_b32_e32 v172, v148
	v_cvt_pk_bf16_f32 v164, v169, v164
	v_pk_mul_f32 v[170:171], v[172:173], v[172:173]
	v_mov_b32_e32 v169, v149
	v_add_f32_e32 v167, v171, v167
	v_pk_fma_f32 v[168:169], v[100:101], v[174:175], v[168:169]
	v_pk_mul_f32 v[172:173], v[148:149], v[148:149]
	v_add_f32_e32 v171, v170, v167
	v_mov_b32_e32 v169, v173
	v_mov_b32_e32 v170, v149
	v_pk_add_f32 v[168:169], v[168:169], v[170:171]
	v_cvt_pk_bf16_f32 v167, v148, v149
	global_store_dwordx4 v[146:147], v[164:167], off offset:256
	ds_bpermute_b32 v146, v162, v168
	ds_bpermute_b32 v147, v162, v169
	s_waitcnt lgkmcnt(0)
	v_pk_add_f32 v[146:147], v[168:169], v[146:147]
	ds_bpermute_b32 v148, v163, v146
	ds_bpermute_b32 v149, v163, v147
	s_and_saveexec_b64 s[12:13], s[40:41]
	s_cbranch_execz .LBB0_317
	v_lshlrev_b64 v[144:145], 8, v[144:145]
	v_lshl_add_u64 v[144:145], s[48:49], 0, v[144:145]
	v_lshl_add_u64 v[144:145], s[30:31], 3, v[144:145]
	s_waitcnt lgkmcnt(0)
	v_pk_add_f32 v[146:147], v[146:147], v[148:149]
	global_store_dwordx2 v[144:145], v[146:147], off
; __device__ __forceinline__ float gelu_f(float x) { const float u = 0.7978845608028654f * (x + 0.044715f * x * x * x); return x * frcp(1.f + fexp2(-2.885390081777927f * u)); }
; __device__ __forceinline__ void st8(bf16_t* p, const float (&v)[8]) { u32x4 w; w.x = pk2(v[0], v[1]); w.y = pk2(v[2], v[3]); w.z = pk2(v[4], v[5]); w.w = pk2(v[6], v[7]); *(u32x4*)p = w; }
;     __device__ __forceinline__ void operator()(const f32x4 (&acc)[2][2][4][2], const Unit& u, int wr, int wc, int fr, int fq) const {
;     ...
;                 for (int m = 0; m < 4; ++m) { const int row = row0 + ai * 128 + m * 16; float s1 = 0.f, s2 = 0.f;
; #pragma unroll
;                     for (int bj = 0; bj < 2; ++bj) { float o[8];
; #pragma unroll
;                         for (int j = 0; j < 4; ++j) { o[j] = gelu_f(acc[ai][bj][m][0][j]); o[4 + j] = gelu_f(acc[ai][bj][m][1][j]); }
; #pragma unroll
;                         for (int j = 0; j < 8; ++j) { s1 += o[j]; s2 += o[j] * o[j]; }
;                         st8(gv + (size_t)row * DM + colt + bj * 128, o); }
.LBB0_317:
	s_or_b64 exec, exec, s[12:13]
	s_waitcnt lgkmcnt(0)
	v_mul_f32_e32 v149, 0x3d372713, v95
	v_mul_f32_e32 v149, v95, v149
	v_fma_f32 v149, v95, v149, v95
	v_mul_f32_e32 v149, 0x3f4c422a, v149
	v_mul_f32_e32 v149, 0xc038aa3b, v149
	v_exp_f32_e32 v149, v149
	v_mul_f32_e32 v148, 0x3d372713, v94
	v_mul_f32_e32 v148, v94, v148
	v_fma_f32 v148, v94, v148, v94
	v_add_f32_e32 v149, 1.0, v149
	v_rcp_f32_e32 v167, v149
	v_mul_f32_e32 v149, 0x3d372713, v91
	v_mul_f32_e32 v149, v91, v149
	v_fma_f32 v149, v91, v149, v91
	v_mul_f32_e32 v149, 0x3f4c422a, v149
	v_mul_f32_e32 v149, 0xc038aa3b, v149
	v_exp_f32_e32 v149, v149
	v_mul_f32_e32 v148, 0x3f4c422a, v148
	v_mul_f32_e32 v148, 0xc038aa3b, v148
	v_exp_f32_e32 v148, v148
	v_add_f32_e32 v149, 1.0, v149
	v_rcp_f32_e32 v164, v149
	v_mul_f32_e32 v149, 0x3d372713, v96
	v_mul_f32_e32 v149, v96, v149
	v_fma_f32 v149, v96, v149, v96
	v_mul_f32_e32 v149, 0x3f4c422a, v149
	v_mul_f32_e32 v149, 0xc038aa3b, v149
	v_exp_f32_e32 v149, v149
	v_add_f32_e32 v148, 1.0, v148
	v_rcp_f32_e32 v166, v148
	v_mul_f32_e32 v148, 0x3d372713, v90
	v_add_f32_e32 v149, 1.0, v149
	v_rcp_f32_e32 v171, v149
	v_mul_f32_e32 v149, 0x3d372713, v92
	v_mul_f32_e32 v149, v92, v149
	v_fma_f32 v149, v92, v149, v92
	v_mul_f32_e32 v149, 0x3f4c422a, v149
	v_mul_f32_e32 v149, 0xc038aa3b, v149
	v_exp_f32_e32 v149, v149
	v_mul_f32_e32 v148, v90, v148
	v_fma_f32 v148, v90, v148, v90
	v_mul_f32_e32 v148, 0x3f4c422a, v148
	v_add_f32_e32 v149, 1.0, v149
	v_rcp_f32_e32 v165, v149
	v_mul_f32_e32 v149, 0x3d372713, v97
	v_mul_f32_e32 v149, v97, v149
	v_fma_f32 v149, v97, v149, v97
	v_mul_f32_e32 v149, 0x3f4c422a, v149
	v_mul_f32_e32 v148, 0xc038aa3b, v148
	v_mul_f32_e32 v149, 0xc038aa3b, v149
	v_exp_f32_e32 v148, v148
	v_exp_f32_e32 v149, v149
	v_mul_f32_e32 v170, v95, v167
	v_fma_f32 v173, v94, v166, 0
	v_add_f32_e32 v148, 1.0, v148
	v_add_f32_e32 v149, 1.0, v149
	v_rcp_f32_e32 v148, v148
	v_rcp_f32_e32 v149, v149
	v_mul_f32_e32 v169, v94, v166
	v_fmac_f32_e32 v173, v95, v167
	v_mul_f32_e32 v174, v170, v170
	v_mov_b32_e32 v166, v90
	v_mov_b32_e32 v167, v97
	v_mul_f32_e32 v172, v96, v171
	v_fmac_f32_e32 v174, v169, v169
	v_pk_mul_f32 v[148:149], v[166:167], v[148:149]
	v_fmac_f32_e32 v174, v172, v172
	v_pk_mul_f32 v[166:167], v[148:149], v[148:149]
	v_fmac_f32_e32 v173, v96, v171
	v_add_f32_e32 v167, v167, v174
	v_add_f32_e32 v171, v149, v173
	v_add_f32_e32 v173, v166, v167
	v_mov_b32_e32 v166, v91
	v_mov_b32_e32 v167, v92
	v_pk_mul_f32 v[166:167], v[166:167], v[164:165]
	v_add_f32_e32 v171, v148, v171
	v_pk_mul_f32 v[164:165], v[166:167], v[166:167]
	v_add_f32_e32 v171, v166, v171
	v_add_f32_e32 v164, v164, v173
	v_add_f32_e32 v186, v165, v164
	v_cvt_pk_bf16_f32 v165, v172, v149
	v_mul_f32_e32 v149, 0x3d372713, v87
	v_mul_f32_e32 v149, v87, v149
	v_fma_f32 v149, v87, v149, v87
	v_mul_f32_e32 v149, 0x3f4c422a, v149
	v_mul_f32_e32 v149, 0xc038aa3b, v149
	v_exp_f32_e32 v149, v149
	v_cvt_pk_bf16_f32 v164, v169, v170
	v_add_f32_e32 v185, v167, v171
	v_cvt_pk_bf16_f32 v166, v148, v166
	v_add_f32_e32 v149, 1.0, v149
	v_rcp_f32_e32 v170, v149
	v_mul_f32_e32 v149, 0x3d372713, v83
	v_mul_f32_e32 v149, v83, v149
	v_fma_f32 v149, v83, v149, v83
	v_mul_f32_e32 v149, 0x3f4c422a, v149
	v_mul_f32_e32 v149, 0xc038aa3b, v149
	v_exp_f32_e32 v149, v149
	v_mul_f32_e32 v148, 0x3d372713, v86
	v_mul_f32_e32 v148, v86, v148
	v_fma_f32 v148, v86, v148, v86
	v_add_f32_e32 v149, 1.0, v149
	v_rcp_f32_e32 v172, v149
	v_mul_f32_e32 v149, 0x3d372713, v88
	v_mul_f32_e32 v149, v88, v149
	v_fma_f32 v149, v88, v149, v88
	v_mul_f32_e32 v149, 0x3f4c422a, v149
	v_mul_f32_e32 v149, 0xc038aa3b, v149
	v_exp_f32_e32 v149, v149
	v_mul_f32_e32 v148, 0x3f4c422a, v148
	v_mul_f32_e32 v168, 0x3d372713, v93
	v_mul_f32_e32 v148, 0xc038aa3b, v148
	v_add_f32_e32 v149, 1.0, v149
	v_rcp_f32_e32 v171, v149
	v_mul_f32_e32 v149, 0x3d372713, v84
	v_mul_f32_e32 v149, v84, v149
	v_fma_f32 v149, v84, v149, v84
	v_mul_f32_e32 v149, 0x3f4c422a, v149
	v_mul_f32_e32 v149, 0xc038aa3b, v149
	v_mul_f32_e32 v168, v93, v168
	v_exp_f32_e32 v148, v148
	v_exp_f32_e32 v149, v149
	v_fma_f32 v168, v93, v168, v93
	v_mul_f32_e32 v168, 0x3f4c422a, v168
	v_mul_f32_e32 v168, 0xc038aa3b, v168
	v_exp_f32_e32 v168, v168
	v_add_f32_e32 v148, 1.0, v148
	v_add_f32_e32 v149, 1.0, v149
	v_rcp_f32_e32 v169, v148
	v_mul_f32_e32 v148, 0x3d372713, v82
	v_rcp_f32_e32 v174, v149
	v_mul_f32_e32 v149, 0x3d372713, v89
	v_mul_f32_e32 v148, v82, v148
	v_mul_f32_e32 v149, v89, v149
	v_fma_f32 v148, v82, v148, v82
	v_fma_f32 v149, v89, v149, v89
	v_add_f32_e32 v168, 1.0, v168
	v_mul_f32_e32 v148, 0x3f4c422a, v148
	v_mul_f32_e32 v149, 0x3f4c422a, v149
	v_mul_f32_e32 v175, 0x3d372713, v85
	v_or_b32_e32 v144, 32, v142
	v_rcp_f32_e32 v168, v168
	v_mul_f32_e32 v148, 0xc038aa3b, v148
	v_mul_f32_e32 v149, 0xc038aa3b, v149
	v_mul_f32_e32 v175, v85, v175
	v_ashrrev_i32_e32 v145, 31, v144
	v_exp_f32_e32 v148, v148
	v_exp_f32_e32 v149, v149
	v_fma_f32 v175, v85, v175, v85
	v_lshlrev_b64 v[146:147], 12, v[144:145]
	v_mul_f32_e32 v175, 0x3f4c422a, v175
	v_lshl_add_u64 v[146:147], s[46:47], 0, v[146:147]
	v_mul_f32_e32 v175, 0xc038aa3b, v175
	v_pk_mov_b32 v[176:177], v[92:93], v[86:87] op_sel:[1,0]
	v_lshl_add_u64 v[146:147], v[146:147], 0, v[0:1]
	v_exp_f32_e32 v175, v175
	v_pk_mul_f32 v[168:169], v[176:177], v[168:169]
	v_add_f32_e32 v148, 1.0, v148
	v_add_f32_e32 v149, 1.0, v149
	v_add_f32_e32 v185, v168, v185
	v_pk_mul_f32 v[176:177], v[168:169], v[168:169]
	v_cvt_pk_bf16_f32 v167, v167, v168
	global_store_dwordx4 v[146:147], v[164:167], off
	v_rcp_f32_e32 v148, v148
	v_rcp_f32_e32 v149, v149
	v_mov_b32_e32 v164, v87
	v_mov_b32_e32 v165, v88
; __device__ __forceinline__ float gelu_f(float x) { const float u = 0.7978845608028654f * (x + 0.044715f * x * x * x); return x * frcp(1.f + fexp2(-2.885390081777927f * u)); }
; __device__ __forceinline__ void st8(bf16_t* p, const float (&v)[8]) { u32x4 w; w.x = pk2(v[0], v[1]); w.y = pk2(v[2], v[3]); w.z = pk2(v[4], v[5]); w.w = pk2(v[6], v[7]); *(u32x4*)p = w; }
;     __device__ __forceinline__ void operator()(const f32x4 (&acc)[2][2][4][2], const Unit& u, int wr, int wc, int fr, int fq) const {
;     ...
;                     for (int bj = 0; bj < 2; ++bj) { float o[8];
; #pragma unroll
;                         for (int j = 0; j < 4; ++j) { o[j] = gelu_f(acc[ai][bj][m][0][j]); o[4 + j] = gelu_f(acc[ai][bj][m][1][j]); }
; #pragma unroll
;                         for (int j = 0; j < 8; ++j) { s1 += o[j]; s2 += o[j] * o[j]; }
;                         st8(gv + (size_t)row * DM + colt + bj * 128, o); }
;                     s1 += __shfl_xor(s1, 16); s2 += __shfl_xor(s2, 16); s1 += __shfl_xor(s1, 32); s2 += __shfl_xor(s2, 32);
;                     if (fq == 0) { float2 w; w.x = s1; w.y = s2; *(float2*)(stats + ((size_t)row * 32 + (pn - 16) * 4 + wc) * 2) = w; }
	v_add_f32_e32 v176, v176, v186
	v_add_f32_e32 v166, v185, v169
	v_pk_mul_f32 v[164:165], v[164:165], v[170:171]
	v_add_f32_e32 v168, v176, v177
	v_add_f32_e32 v170, v164, v166
	v_pk_mul_f32 v[166:167], v[164:165], v[164:165]
	v_add_f32_e32 v175, 1.0, v175
	v_add_f32_e32 v166, v166, v168
	v_rcp_f32_e32 v175, v175
	v_add_f32_e32 v168, v165, v170
	v_add_f32_e32 v170, v167, v166
	v_mov_b32_e32 v166, v82
	v_mov_b32_e32 v167, v89
	v_pk_mul_f32 v[148:149], v[166:167], v[148:149]
	v_mul_f32_e32 v173, v83, v172
	v_pk_mul_f32 v[166:167], v[148:149], v[148:149]
	v_add_f32_e32 v168, v149, v168
	v_add_f32_e32 v167, v167, v170
	v_add_f32_e32 v168, v148, v168
	v_add_f32_e32 v167, v166, v167
	v_cvt_pk_bf16_f32 v165, v165, v149
	v_cvt_pk_bf16_f32 v166, v148, v173
	v_pk_mul_f32 v[148:149], v[84:85], v[174:175]
	v_fmac_f32_e32 v168, v83, v172
	v_mov_b32_e32 v172, v148
	v_cvt_pk_bf16_f32 v164, v169, v164
	v_pk_mul_f32 v[170:171], v[172:173], v[172:173]
	v_mov_b32_e32 v169, v149
	v_add_f32_e32 v167, v171, v167
	v_pk_fma_f32 v[168:169], v[84:85], v[174:175], v[168:169]
	v_pk_mul_f32 v[172:173], v[148:149], v[148:149]
	v_add_f32_e32 v171, v170, v167
	v_mov_b32_e32 v169, v173
	v_mov_b32_e32 v170, v149
	v_pk_add_f32 v[168:169], v[168:169], v[170:171]
	v_cvt_pk_bf16_f32 v167, v148, v149
	global_store_dwordx4 v[146:147], v[164:167], off offset:256
	ds_bpermute_b32 v146, v162, v168
	ds_bpermute_b32 v147, v162, v169
	s_waitcnt lgkmcnt(0)
	v_pk_add_f32 v[146:147], v[168:169], v[146:147]
	ds_bpermute_b32 v148, v163, v146
	ds_bpermute_b32 v149, v163, v147
	s_and_saveexec_b64 s[12:13], s[40:41]
	s_cbranch_execz .LBB0_319
	v_lshlrev_b64 v[144:145], 8, v[144:145]
	v_lshl_add_u64 v[144:145], s[48:49], 0, v[144:145]
	v_lshl_add_u64 v[144:145], s[30:31], 3, v[144:145]
	s_waitcnt lgkmcnt(0)
	v_pk_add_f32 v[146:147], v[146:147], v[148:149]
	global_store_dwordx2 v[144:145], v[146:147], off
.LBB0_319:
	s_or_b64 exec, exec, s[12:13]
	s_waitcnt lgkmcnt(0)
	v_mul_f32_e32 v149, 0x3d372713, v79
	v_mul_f32_e32 v149, v79, v149
	v_fma_f32 v149, v79, v149, v79
	v_mul_f32_e32 v149, 0x3f4c422a, v149
	v_mul_f32_e32 v149, 0xc038aa3b, v149
	v_exp_f32_e32 v149, v149
	v_mul_f32_e32 v148, 0x3d372713, v78
	v_mul_f32_e32 v148, v78, v148
	v_fma_f32 v148, v78, v148, v78
	v_add_f32_e32 v149, 1.0, v149
	v_rcp_f32_e32 v167, v149
	v_mul_f32_e32 v149, 0x3d372713, v75
	v_mul_f32_e32 v149, v75, v149
	v_fma_f32 v149, v75, v149, v75
	v_mul_f32_e32 v149, 0x3f4c422a, v149
	v_mul_f32_e32 v149, 0xc038aa3b, v149
	v_exp_f32_e32 v149, v149
	v_mul_f32_e32 v148, 0x3f4c422a, v148
	v_mul_f32_e32 v148, 0xc038aa3b, v148
	v_exp_f32_e32 v148, v148
	v_add_f32_e32 v149, 1.0, v149
	v_rcp_f32_e32 v164, v149
	v_mul_f32_e32 v149, 0x3d372713, v80
	v_mul_f32_e32 v149, v80, v149
	v_fma_f32 v149, v80, v149, v80
	v_mul_f32_e32 v149, 0x3f4c422a, v149
	v_mul_f32_e32 v149, 0xc038aa3b, v149
	v_exp_f32_e32 v149, v149
	v_add_f32_e32 v148, 1.0, v148
	v_rcp_f32_e32 v166, v148
	v_mul_f32_e32 v148, 0x3d372713, v74
	v_add_f32_e32 v149, 1.0, v149
	v_rcp_f32_e32 v171, v149
	v_mul_f32_e32 v149, 0x3d372713, v76
	v_mul_f32_e32 v149, v76, v149
	v_fma_f32 v149, v76, v149, v76
	v_mul_f32_e32 v149, 0x3f4c422a, v149
	v_mul_f32_e32 v149, 0xc038aa3b, v149
	v_exp_f32_e32 v149, v149
	v_mul_f32_e32 v148, v74, v148
	v_fma_f32 v148, v74, v148, v74
	v_mul_f32_e32 v148, 0x3f4c422a, v148
	v_add_f32_e32 v149, 1.0, v149
	v_rcp_f32_e32 v165, v149
	v_mul_f32_e32 v149, 0x3d372713, v81
	v_mul_f32_e32 v149, v81, v149
	v_fma_f32 v149, v81, v149, v81
	v_mul_f32_e32 v149, 0x3f4c422a, v149
	v_mul_f32_e32 v148, 0xc038aa3b, v148
	v_mul_f32_e32 v149, 0xc038aa3b, v149
	v_exp_f32_e32 v148, v148
	v_exp_f32_e32 v149, v149
	v_mul_f32_e32 v170, v79, v167
	v_fma_f32 v173, v78, v166, 0
	v_add_f32_e32 v148, 1.0, v148
	v_add_f32_e32 v149, 1.0, v149
	v_rcp_f32_e32 v148, v148
	v_rcp_f32_e32 v149, v149
	v_mul_f32_e32 v169, v78, v166
	v_fmac_f32_e32 v173, v79, v167
	v_mul_f32_e32 v174, v170, v170
	v_mov_b32_e32 v166, v74
	v_mov_b32_e32 v167, v81
	v_mul_f32_e32 v172, v80, v171
	v_fmac_f32_e32 v174, v169, v169
	v_pk_mul_f32 v[148:149], v[166:167], v[148:149]
	v_fmac_f32_e32 v174, v172, v172
	v_pk_mul_f32 v[166:167], v[148:149], v[148:149]
	v_fmac_f32_e32 v173, v80, v171
	v_add_f32_e32 v167, v167, v174
	v_add_f32_e32 v171, v149, v173
	v_add_f32_e32 v173, v166, v167
	v_mov_b32_e32 v166, v75
	v_mov_b32_e32 v167, v76
	v_pk_mul_f32 v[166:167], v[166:167], v[164:165]
	v_add_f32_e32 v171, v148, v171
	v_pk_mul_f32 v[164:165], v[166:167], v[166:167]
	v_add_f32_e32 v171, v166, v171
	v_add_f32_e32 v164, v164, v173
	v_add_f32_e32 v186, v165, v164
	v_cvt_pk_bf16_f32 v165, v172, v149
	v_mul_f32_e32 v149, 0x3d372713, v71
	v_mul_f32_e32 v149, v71, v149
	v_fma_f32 v149, v71, v149, v71
	v_mul_f32_e32 v149, 0x3f4c422a, v149
	v_mul_f32_e32 v149, 0xc038aa3b, v149
	v_exp_f32_e32 v149, v149
	v_cvt_pk_bf16_f32 v164, v169, v170
	v_add_f32_e32 v185, v167, v171
	v_cvt_pk_bf16_f32 v166, v148, v166
	v_add_f32_e32 v149, 1.0, v149
	v_rcp_f32_e32 v170, v149
	v_mul_f32_e32 v149, 0x3d372713, v67
	v_mul_f32_e32 v149, v67, v149
	v_fma_f32 v149, v67, v149, v67
	v_mul_f32_e32 v149, 0x3f4c422a, v149
	v_mul_f32_e32 v149, 0xc038aa3b, v149
	v_exp_f32_e32 v149, v149
	v_mul_f32_e32 v148, 0x3d372713, v70
	v_mul_f32_e32 v148, v70, v148
	v_fma_f32 v148, v70, v148, v70
	v_add_f32_e32 v149, 1.0, v149
	v_rcp_f32_e32 v172, v149
	v_mul_f32_e32 v149, 0x3d372713, v72
	v_mul_f32_e32 v149, v72, v149
	v_fma_f32 v149, v72, v149, v72
	v_mul_f32_e32 v149, 0x3f4c422a, v149
	v_mul_f32_e32 v149, 0xc038aa3b, v149
	v_exp_f32_e32 v149, v149
	v_mul_f32_e32 v148, 0x3f4c422a, v148
	v_mul_f32_e32 v168, 0x3d372713, v77
	v_mul_f32_e32 v148, 0xc038aa3b, v148
; __device__ __forceinline__ float gelu_f(float x) { const float u = 0.7978845608028654f * (x + 0.044715f * x * x * x); return x * frcp(1.f + fexp2(-2.885390081777927f * u)); }
; __device__ __forceinline__ void st8(bf16_t* p, const float (&v)[8]) { u32x4 w; w.x = pk2(v[0], v[1]); w.y = pk2(v[2], v[3]); w.z = pk2(v[4], v[5]); w.w = pk2(v[6], v[7]); *(u32x4*)p = w; }
;     __device__ __forceinline__ void operator()(const f32x4 (&acc)[2][2][4][2], const Unit& u, int wr, int wc, int fr, int fq) const {
;     ...
;                     for (int bj = 0; bj < 2; ++bj) { float o[8];
; #pragma unroll
;                         for (int j = 0; j < 4; ++j) { o[j] = gelu_f(acc[ai][bj][m][0][j]); o[4 + j] = gelu_f(acc[ai][bj][m][1][j]); }
; #pragma unroll
;                         for (int j = 0; j < 8; ++j) { s1 += o[j]; s2 += o[j] * o[j]; }
;                         st8(gv + (size_t)row * DM + colt + bj * 128, o); }
;                     s1 += __shfl_xor(s1, 16); s2 += __shfl_xor(s2, 16); s1 += __shfl_xor(s1, 32); s2 += __shfl_xor(s2, 32);
;                     if (fq == 0) { float2 w; w.x = s1; w.y = s2; *(float2*)(stats + ((size_t)row * 32 + (pn - 16) * 4 + wc) * 2) = w; }
	v_add_f32_e32 v149, 1.0, v149
	v_rcp_f32_e32 v171, v149
	v_mul_f32_e32 v149, 0x3d372713, v68
	v_mul_f32_e32 v149, v68, v149
	v_fma_f32 v149, v68, v149, v68
	v_mul_f32_e32 v149, 0x3f4c422a, v149
	v_mul_f32_e32 v149, 0xc038aa3b, v149
	v_mul_f32_e32 v168, v77, v168
	v_exp_f32_e32 v148, v148
	v_exp_f32_e32 v149, v149
	v_fma_f32 v168, v77, v168, v77
	v_mul_f32_e32 v168, 0x3f4c422a, v168
	v_mul_f32_e32 v168, 0xc038aa3b, v168
	v_exp_f32_e32 v168, v168
	v_add_f32_e32 v148, 1.0, v148
	v_add_f32_e32 v149, 1.0, v149
	v_rcp_f32_e32 v169, v148
	v_mul_f32_e32 v148, 0x3d372713, v66
	v_rcp_f32_e32 v174, v149
	v_mul_f32_e32 v149, 0x3d372713, v73
	v_mul_f32_e32 v148, v66, v148
	v_mul_f32_e32 v149, v73, v149
	v_fma_f32 v148, v66, v148, v66
	v_fma_f32 v149, v73, v149, v73
	v_add_f32_e32 v168, 1.0, v168
	v_mul_f32_e32 v148, 0x3f4c422a, v148
	v_mul_f32_e32 v149, 0x3f4c422a, v149
	v_mul_f32_e32 v175, 0x3d372713, v69
	v_or_b32_e32 v144, 48, v142
	v_rcp_f32_e32 v168, v168
	v_mul_f32_e32 v148, 0xc038aa3b, v148
	v_mul_f32_e32 v149, 0xc038aa3b, v149
	v_mul_f32_e32 v175, v69, v175
	v_ashrrev_i32_e32 v145, 31, v144
	v_exp_f32_e32 v148, v148
	v_exp_f32_e32 v149, v149
	v_fma_f32 v175, v69, v175, v69
	v_lshlrev_b64 v[146:147], 12, v[144:145]
	v_mul_f32_e32 v175, 0x3f4c422a, v175
	v_lshl_add_u64 v[146:147], s[46:47], 0, v[146:147]
	v_mul_f32_e32 v175, 0xc038aa3b, v175
	v_pk_mov_b32 v[176:177], v[76:77], v[70:71] op_sel:[1,0]
	v_lshl_add_u64 v[146:147], v[146:147], 0, v[0:1]
	v_exp_f32_e32 v175, v175
	v_pk_mul_f32 v[168:169], v[176:177], v[168:169]
	v_add_f32_e32 v148, 1.0, v148
	v_add_f32_e32 v149, 1.0, v149
	v_add_f32_e32 v185, v168, v185
	v_pk_mul_f32 v[176:177], v[168:169], v[168:169]
	v_cvt_pk_bf16_f32 v167, v167, v168
	global_store_dwordx4 v[146:147], v[164:167], off
	v_rcp_f32_e32 v148, v148
	v_rcp_f32_e32 v149, v149
	v_mov_b32_e32 v164, v71
	v_mov_b32_e32 v165, v72
	v_add_f32_e32 v176, v176, v186
	v_add_f32_e32 v166, v185, v169
	v_pk_mul_f32 v[164:165], v[164:165], v[170:171]
	v_add_f32_e32 v168, v176, v177
	v_add_f32_e32 v170, v164, v166
	v_pk_mul_f32 v[166:167], v[164:165], v[164:165]
	v_add_f32_e32 v175, 1.0, v175
	v_add_f32_e32 v166, v166, v168
	v_rcp_f32_e32 v175, v175
	v_add_f32_e32 v168, v165, v170
	v_add_f32_e32 v170, v167, v166
	v_mov_b32_e32 v166, v66
	v_mov_b32_e32 v167, v73
	v_pk_mul_f32 v[148:149], v[166:167], v[148:149]
	v_mul_f32_e32 v173, v67, v172
	v_pk_mul_f32 v[166:167], v[148:149], v[148:149]
	v_add_f32_e32 v168, v149, v168
	v_add_f32_e32 v167, v167, v170
	v_add_f32_e32 v168, v148, v168
	v_add_f32_e32 v167, v166, v167
	v_cvt_pk_bf16_f32 v165, v165, v149
	v_cvt_pk_bf16_f32 v166, v148, v173
	v_pk_mul_f32 v[148:149], v[68:69], v[174:175]
	v_fmac_f32_e32 v168, v67, v172
	v_mov_b32_e32 v172, v148
	v_cvt_pk_bf16_f32 v164, v169, v164
	v_pk_mul_f32 v[170:171], v[172:173], v[172:173]
	v_mov_b32_e32 v169, v149
	v_add_f32_e32 v167, v171, v167
	v_pk_fma_f32 v[168:169], v[68:69], v[174:175], v[168:169]
	v_pk_mul_f32 v[172:173], v[148:149], v[148:149]
	v_add_f32_e32 v171, v170, v167
	v_mov_b32_e32 v169, v173
	v_mov_b32_e32 v170, v149
	v_pk_add_f32 v[168:169], v[168:169], v[170:171]
	v_cvt_pk_bf16_f32 v167, v148, v149
	global_store_dwordx4 v[146:147], v[164:167], off offset:256
	ds_bpermute_b32 v146, v162, v168
	ds_bpermute_b32 v147, v162, v169
	s_waitcnt lgkmcnt(0)
	v_pk_add_f32 v[146:147], v[168:169], v[146:147]
	ds_bpermute_b32 v148, v163, v146
	ds_bpermute_b32 v149, v163, v147
	s_and_saveexec_b64 s[12:13], s[40:41]
	s_cbranch_execz .LBB0_321
	v_lshlrev_b64 v[144:145], 8, v[144:145]
	v_lshl_add_u64 v[144:145], s[48:49], 0, v[144:145]
	v_lshl_add_u64 v[144:145], s[30:31], 3, v[144:145]
	s_waitcnt lgkmcnt(0)
	v_pk_add_f32 v[146:147], v[146:147], v[148:149]
	global_store_dwordx2 v[144:145], v[146:147], off
.LBB0_321:
	s_or_b64 exec, exec, s[12:13]
	s_waitcnt lgkmcnt(0)
	v_mul_f32_e32 v149, 0x3d372713, v63
	v_mul_f32_e32 v149, v63, v149
	v_fma_f32 v149, v63, v149, v63
	v_mul_f32_e32 v149, 0x3f4c422a, v149
	v_mul_f32_e32 v149, 0xc038aa3b, v149
	v_exp_f32_e32 v149, v149
	v_mul_f32_e32 v148, 0x3d372713, v62
	v_mul_f32_e32 v148, v62, v148
	v_fma_f32 v148, v62, v148, v62
	v_add_f32_e32 v149, 1.0, v149
	v_rcp_f32_e32 v167, v149
	v_mul_f32_e32 v149, 0x3d372713, v59
	v_mul_f32_e32 v149, v59, v149
	v_fma_f32 v149, v59, v149, v59
	v_mul_f32_e32 v149, 0x3f4c422a, v149
	v_mul_f32_e32 v149, 0xc038aa3b, v149
	v_exp_f32_e32 v149, v149
	v_mul_f32_e32 v148, 0x3f4c422a, v148
	v_mul_f32_e32 v148, 0xc038aa3b, v148
	v_exp_f32_e32 v148, v148
	v_add_f32_e32 v149, 1.0, v149
	v_rcp_f32_e32 v164, v149
	v_mul_f32_e32 v149, 0x3d372713, v64
	v_mul_f32_e32 v149, v64, v149
	v_fma_f32 v149, v64, v149, v64
	v_mul_f32_e32 v149, 0x3f4c422a, v149
	v_mul_f32_e32 v149, 0xc038aa3b, v149
	v_exp_f32_e32 v149, v149
	v_add_f32_e32 v148, 1.0, v148
	v_rcp_f32_e32 v166, v148
	v_mul_f32_e32 v148, 0x3d372713, v58
	v_add_f32_e32 v149, 1.0, v149
	v_rcp_f32_e32 v171, v149
	v_mul_f32_e32 v149, 0x3d372713, v60
	v_mul_f32_e32 v149, v60, v149
	v_fma_f32 v149, v60, v149, v60
	v_mul_f32_e32 v149, 0x3f4c422a, v149
	v_mul_f32_e32 v149, 0xc038aa3b, v149
	v_exp_f32_e32 v149, v149
	v_mul_f32_e32 v148, v58, v148
	v_fma_f32 v148, v58, v148, v58
	v_mul_f32_e32 v148, 0x3f4c422a, v148
	v_add_f32_e32 v149, 1.0, v149
	v_rcp_f32_e32 v165, v149
	v_mul_f32_e32 v149, 0x3d372713, v65
	v_mul_f32_e32 v149, v65, v149
	v_fma_f32 v149, v65, v149, v65
	v_mul_f32_e32 v149, 0x3f4c422a, v149
	v_mul_f32_e32 v148, 0xc038aa3b, v148
	v_mul_f32_e32 v149, 0xc038aa3b, v149
	v_exp_f32_e32 v148, v148
	v_exp_f32_e32 v149, v149
	v_mul_f32_e32 v170, v63, v167
	v_fma_f32 v173, v62, v166, 0
	v_add_f32_e32 v148, 1.0, v148
	v_add_f32_e32 v149, 1.0, v149
; __device__ __forceinline__ float gelu_f(float x) { const float u = 0.7978845608028654f * (x + 0.044715f * x * x * x); return x * frcp(1.f + fexp2(-2.885390081777927f * u)); }
; __device__ __forceinline__ void st8(bf16_t* p, const float (&v)[8]) { u32x4 w; w.x = pk2(v[0], v[1]); w.y = pk2(v[2], v[3]); w.z = pk2(v[4], v[5]); w.w = pk2(v[6], v[7]); *(u32x4*)p = w; }
;     __device__ __forceinline__ void operator()(const f32x4 (&acc)[2][2][4][2], const Unit& u, int wr, int wc, int fr, int fq) const {
;     ...
;                     for (int bj = 0; bj < 2; ++bj) { float o[8];
; #pragma unroll
;                         for (int j = 0; j < 4; ++j) { o[j] = gelu_f(acc[ai][bj][m][0][j]); o[4 + j] = gelu_f(acc[ai][bj][m][1][j]); }
; #pragma unroll
;                         for (int j = 0; j < 8; ++j) { s1 += o[j]; s2 += o[j] * o[j]; }
;                         st8(gv + (size_t)row * DM + colt + bj * 128, o); }
;                     s1 += __shfl_xor(s1, 16); s2 += __shfl_xor(s2, 16); s1 += __shfl_xor(s1, 32); s2 += __shfl_xor(s2, 32);
;                     if (fq == 0) { float2 w; w.x = s1; w.y = s2; *(float2*)(stats + ((size_t)row * 32 + (pn - 16) * 4 + wc) * 2) = w; }
	v_rcp_f32_e32 v148, v148
	v_rcp_f32_e32 v149, v149
	v_mul_f32_e32 v169, v62, v166
	v_fmac_f32_e32 v173, v63, v167
	v_mul_f32_e32 v174, v170, v170
	v_mov_b32_e32 v166, v58
	v_mov_b32_e32 v167, v65
	v_mul_f32_e32 v172, v64, v171
	v_fmac_f32_e32 v174, v169, v169
	v_pk_mul_f32 v[148:149], v[166:167], v[148:149]
	v_fmac_f32_e32 v174, v172, v172
	v_pk_mul_f32 v[166:167], v[148:149], v[148:149]
	v_fmac_f32_e32 v173, v64, v171
	v_add_f32_e32 v167, v167, v174
	v_add_f32_e32 v171, v149, v173
	v_add_f32_e32 v173, v166, v167
	v_mov_b32_e32 v166, v59
	v_mov_b32_e32 v167, v60
	v_pk_mul_f32 v[166:167], v[166:167], v[164:165]
	v_add_f32_e32 v171, v148, v171
	v_pk_mul_f32 v[164:165], v[166:167], v[166:167]
	v_add_f32_e32 v171, v166, v171
	v_add_f32_e32 v164, v164, v173
	v_add_f32_e32 v186, v165, v164
	v_cvt_pk_bf16_f32 v165, v172, v149
	v_mul_f32_e32 v149, 0x3d372713, v55
	v_mul_f32_e32 v149, v55, v149
	v_fma_f32 v149, v55, v149, v55
	v_mul_f32_e32 v149, 0x3f4c422a, v149
	v_mul_f32_e32 v149, 0xc038aa3b, v149
	v_exp_f32_e32 v149, v149
	v_cvt_pk_bf16_f32 v164, v169, v170
	v_add_f32_e32 v185, v167, v171
	v_cvt_pk_bf16_f32 v166, v148, v166
	v_add_f32_e32 v149, 1.0, v149
	v_rcp_f32_e32 v170, v149
	v_mul_f32_e32 v149, 0x3d372713, v51
	v_mul_f32_e32 v149, v51, v149
	v_fma_f32 v149, v51, v149, v51
	v_mul_f32_e32 v149, 0x3f4c422a, v149
	v_mul_f32_e32 v149, 0xc038aa3b, v149
	v_exp_f32_e32 v149, v149
	v_mul_f32_e32 v148, 0x3d372713, v54
	v_mul_f32_e32 v148, v54, v148
	v_fma_f32 v148, v54, v148, v54
	v_add_f32_e32 v149, 1.0, v149
	v_rcp_f32_e32 v172, v149
	v_mul_f32_e32 v149, 0x3d372713, v56
	v_mul_f32_e32 v149, v56, v149
	v_fma_f32 v149, v56, v149, v56
	v_mul_f32_e32 v149, 0x3f4c422a, v149
	v_mul_f32_e32 v149, 0xc038aa3b, v149
	v_exp_f32_e32 v149, v149
	v_mul_f32_e32 v148, 0x3f4c422a, v148
	v_mul_f32_e32 v168, 0x3d372713, v61
	v_mul_f32_e32 v148, 0xc038aa3b, v148
	v_add_f32_e32 v149, 1.0, v149
	v_rcp_f32_e32 v171, v149
	v_mul_f32_e32 v149, 0x3d372713, v52
	v_mul_f32_e32 v149, v52, v149
	v_fma_f32 v149, v52, v149, v52
	v_mul_f32_e32 v149, 0x3f4c422a, v149
	v_mul_f32_e32 v149, 0xc038aa3b, v149
	v_mul_f32_e32 v168, v61, v168
	v_exp_f32_e32 v148, v148
	v_exp_f32_e32 v149, v149
	v_fma_f32 v168, v61, v168, v61
	v_mul_f32_e32 v168, 0x3f4c422a, v168
	v_mul_f32_e32 v168, 0xc038aa3b, v168
	v_exp_f32_e32 v168, v168
	v_add_f32_e32 v148, 1.0, v148
	v_add_f32_e32 v149, 1.0, v149
	v_rcp_f32_e32 v169, v148
	v_mul_f32_e32 v148, 0x3d372713, v50
	v_rcp_f32_e32 v174, v149
	v_mul_f32_e32 v149, 0x3d372713, v57
	v_mul_f32_e32 v148, v50, v148
	v_mul_f32_e32 v149, v57, v149
	v_fma_f32 v148, v50, v148, v50
	v_fma_f32 v149, v57, v149, v57
	v_add_f32_e32 v168, 1.0, v168
	v_mul_f32_e32 v148, 0x3f4c422a, v148
	v_mul_f32_e32 v149, 0x3f4c422a, v149
	v_mul_f32_e32 v175, 0x3d372713, v53
	v_add_u32_e32 v144, 0x80, v142
	v_rcp_f32_e32 v168, v168
	v_mul_f32_e32 v148, 0xc038aa3b, v148
	v_mul_f32_e32 v149, 0xc038aa3b, v149
	v_mul_f32_e32 v175, v53, v175
	v_ashrrev_i32_e32 v145, 31, v144
	v_exp_f32_e32 v148, v148
	v_exp_f32_e32 v149, v149
	v_fma_f32 v175, v53, v175, v53
	v_lshlrev_b64 v[146:147], 12, v[144:145]
	v_mul_f32_e32 v175, 0x3f4c422a, v175
	v_lshl_add_u64 v[146:147], s[46:47], 0, v[146:147]
	v_mul_f32_e32 v175, 0xc038aa3b, v175
	v_pk_mov_b32 v[176:177], v[60:61], v[54:55] op_sel:[1,0]
	v_lshl_add_u64 v[146:147], v[146:147], 0, v[0:1]
	v_exp_f32_e32 v175, v175
	v_pk_mul_f32 v[168:169], v[176:177], v[168:169]
	v_add_f32_e32 v148, 1.0, v148
	v_add_f32_e32 v149, 1.0, v149
	v_add_f32_e32 v185, v168, v185
	v_pk_mul_f32 v[176:177], v[168:169], v[168:169]
	v_cvt_pk_bf16_f32 v167, v167, v168
	global_store_dwordx4 v[146:147], v[164:167], off
	v_rcp_f32_e32 v148, v148
	v_rcp_f32_e32 v149, v149
	v_mov_b32_e32 v164, v55
	v_mov_b32_e32 v165, v56
	v_add_f32_e32 v176, v176, v186
	v_add_f32_e32 v166, v185, v169
	v_pk_mul_f32 v[164:165], v[164:165], v[170:171]
	v_add_f32_e32 v168, v176, v177
	v_add_f32_e32 v170, v164, v166
	v_pk_mul_f32 v[166:167], v[164:165], v[164:165]
	v_add_f32_e32 v175, 1.0, v175
	v_add_f32_e32 v166, v166, v168
	v_rcp_f32_e32 v175, v175
	v_add_f32_e32 v168, v165, v170
	v_add_f32_e32 v170, v167, v166
	v_mov_b32_e32 v166, v50
	v_mov_b32_e32 v167, v57
	v_pk_mul_f32 v[148:149], v[166:167], v[148:149]
	v_mul_f32_e32 v173, v51, v172
	v_pk_mul_f32 v[166:167], v[148:149], v[148:149]
	v_add_f32_e32 v168, v149, v168
	v_add_f32_e32 v167, v167, v170
	v_add_f32_e32 v168, v148, v168
	v_add_f32_e32 v167, v166, v167
	v_cvt_pk_bf16_f32 v165, v165, v149
	v_cvt_pk_bf16_f32 v166, v148, v173
	v_pk_mul_f32 v[148:149], v[52:53], v[174:175]
	v_fmac_f32_e32 v168, v51, v172
	v_mov_b32_e32 v172, v148
	v_cvt_pk_bf16_f32 v164, v169, v164
	v_pk_mul_f32 v[170:171], v[172:173], v[172:173]
	v_mov_b32_e32 v169, v149
	v_add_f32_e32 v167, v171, v167
	v_pk_fma_f32 v[168:169], v[52:53], v[174:175], v[168:169]
	v_pk_mul_f32 v[172:173], v[148:149], v[148:149]
	v_add_f32_e32 v171, v170, v167
	v_mov_b32_e32 v169, v173
	v_mov_b32_e32 v170, v149
	v_pk_add_f32 v[168:169], v[168:169], v[170:171]
	v_cvt_pk_bf16_f32 v167, v148, v149
	global_store_dwordx4 v[146:147], v[164:167], off offset:256
	ds_bpermute_b32 v146, v162, v168
	ds_bpermute_b32 v147, v162, v169
	s_waitcnt lgkmcnt(0)
	v_pk_add_f32 v[146:147], v[168:169], v[146:147]
	ds_bpermute_b32 v148, v163, v146
	ds_bpermute_b32 v149, v163, v147
	s_and_saveexec_b64 s[12:13], s[40:41]
	s_cbranch_execz .LBB0_323
	v_lshlrev_b64 v[144:145], 8, v[144:145]
	v_lshl_add_u64 v[144:145], s[48:49], 0, v[144:145]
	v_lshl_add_u64 v[144:145], s[30:31], 3, v[144:145]
	s_waitcnt lgkmcnt(0)
	v_pk_add_f32 v[146:147], v[146:147], v[148:149]
	global_store_dwordx2 v[144:145], v[146:147], off
; __device__ __forceinline__ float gelu_f(float x) { const float u = 0.7978845608028654f * (x + 0.044715f * x * x * x); return x * frcp(1.f + fexp2(-2.885390081777927f * u)); }
; __device__ __forceinline__ void st8(bf16_t* p, const float (&v)[8]) { u32x4 w; w.x = pk2(v[0], v[1]); w.y = pk2(v[2], v[3]); w.z = pk2(v[4], v[5]); w.w = pk2(v[6], v[7]); *(u32x4*)p = w; }
;     __device__ __forceinline__ void operator()(const f32x4 (&acc)[2][2][4][2], const Unit& u, int wr, int wc, int fr, int fq) const {
;     ...
;                 for (int m = 0; m < 4; ++m) { const int row = row0 + ai * 128 + m * 16; float s1 = 0.f, s2 = 0.f;
; #pragma unroll
;                     for (int bj = 0; bj < 2; ++bj) { float o[8];
; #pragma unroll
;                         for (int j = 0; j < 4; ++j) { o[j] = gelu_f(acc[ai][bj][m][0][j]); o[4 + j] = gelu_f(acc[ai][bj][m][1][j]); }
; #pragma unroll
;                         for (int j = 0; j < 8; ++j) { s1 += o[j]; s2 += o[j] * o[j]; }
;                         st8(gv + (size_t)row * DM + colt + bj * 128, o); }
.LBB0_323:
	s_or_b64 exec, exec, s[12:13]
	s_waitcnt lgkmcnt(0)
	v_mul_f32_e32 v149, 0x3d372713, v47
	v_mul_f32_e32 v149, v47, v149
	v_fma_f32 v149, v47, v149, v47
	v_mul_f32_e32 v149, 0x3f4c422a, v149
	v_mul_f32_e32 v149, 0xc038aa3b, v149
	v_exp_f32_e32 v149, v149
	v_mul_f32_e32 v148, 0x3d372713, v46
	v_mul_f32_e32 v148, v46, v148
	v_fma_f32 v148, v46, v148, v46
	v_add_f32_e32 v149, 1.0, v149
	v_rcp_f32_e32 v167, v149
	v_mul_f32_e32 v149, 0x3d372713, v43
	v_mul_f32_e32 v149, v43, v149
	v_fma_f32 v149, v43, v149, v43
	v_mul_f32_e32 v149, 0x3f4c422a, v149
	v_mul_f32_e32 v149, 0xc038aa3b, v149
	v_exp_f32_e32 v149, v149
	v_mul_f32_e32 v148, 0x3f4c422a, v148
	v_mul_f32_e32 v148, 0xc038aa3b, v148
	v_exp_f32_e32 v148, v148
	v_add_f32_e32 v149, 1.0, v149
	v_rcp_f32_e32 v164, v149
	v_mul_f32_e32 v149, 0x3d372713, v48
	v_mul_f32_e32 v149, v48, v149
	v_fma_f32 v149, v48, v149, v48
	v_mul_f32_e32 v149, 0x3f4c422a, v149
	v_mul_f32_e32 v149, 0xc038aa3b, v149
	v_exp_f32_e32 v149, v149
	v_add_f32_e32 v148, 1.0, v148
	v_rcp_f32_e32 v166, v148
	v_mul_f32_e32 v148, 0x3d372713, v42
	v_add_f32_e32 v149, 1.0, v149
	v_rcp_f32_e32 v171, v149
	v_mul_f32_e32 v149, 0x3d372713, v44
	v_mul_f32_e32 v149, v44, v149
	v_fma_f32 v149, v44, v149, v44
	v_mul_f32_e32 v149, 0x3f4c422a, v149
	v_mul_f32_e32 v149, 0xc038aa3b, v149
	v_exp_f32_e32 v149, v149
	v_mul_f32_e32 v148, v42, v148
	v_fma_f32 v148, v42, v148, v42
	v_mul_f32_e32 v148, 0x3f4c422a, v148
	v_add_f32_e32 v149, 1.0, v149
	v_rcp_f32_e32 v165, v149
	v_mul_f32_e32 v149, 0x3d372713, v49
	v_mul_f32_e32 v149, v49, v149
	v_fma_f32 v149, v49, v149, v49
	v_mul_f32_e32 v149, 0x3f4c422a, v149
	v_mul_f32_e32 v148, 0xc038aa3b, v148
	v_mul_f32_e32 v149, 0xc038aa3b, v149
	v_exp_f32_e32 v148, v148
	v_exp_f32_e32 v149, v149
	v_mul_f32_e32 v170, v47, v167
	v_fma_f32 v173, v46, v166, 0
	v_add_f32_e32 v148, 1.0, v148
	v_add_f32_e32 v149, 1.0, v149
	v_rcp_f32_e32 v148, v148
	v_rcp_f32_e32 v149, v149
	v_mul_f32_e32 v169, v46, v166
	v_fmac_f32_e32 v173, v47, v167
	v_mul_f32_e32 v174, v170, v170
	v_mov_b32_e32 v166, v42
	v_mov_b32_e32 v167, v49
	v_mul_f32_e32 v172, v48, v171
	v_fmac_f32_e32 v174, v169, v169
	v_pk_mul_f32 v[148:149], v[166:167], v[148:149]
	v_fmac_f32_e32 v174, v172, v172
	v_pk_mul_f32 v[166:167], v[148:149], v[148:149]
	v_fmac_f32_e32 v173, v48, v171
	v_add_f32_e32 v167, v167, v174
	v_add_f32_e32 v171, v149, v173
	v_add_f32_e32 v173, v166, v167
	v_mov_b32_e32 v166, v43
	v_mov_b32_e32 v167, v44
	v_pk_mul_f32 v[166:167], v[166:167], v[164:165]
	v_add_f32_e32 v171, v148, v171
	v_pk_mul_f32 v[164:165], v[166:167], v[166:167]
	v_add_f32_e32 v171, v166, v171
	v_add_f32_e32 v164, v164, v173
	v_add_f32_e32 v186, v165, v164
	v_cvt_pk_bf16_f32 v165, v172, v149
	v_mul_f32_e32 v149, 0x3d372713, v39
	v_mul_f32_e32 v149, v39, v149
	v_fma_f32 v149, v39, v149, v39
	v_mul_f32_e32 v149, 0x3f4c422a, v149
	v_mul_f32_e32 v149, 0xc038aa3b, v149
	v_exp_f32_e32 v149, v149
	v_cvt_pk_bf16_f32 v164, v169, v170
	v_add_f32_e32 v185, v167, v171
	v_cvt_pk_bf16_f32 v166, v148, v166
	v_add_f32_e32 v149, 1.0, v149
	v_rcp_f32_e32 v170, v149
	v_mul_f32_e32 v149, 0x3d372713, v35
	v_mul_f32_e32 v149, v35, v149
	v_fma_f32 v149, v35, v149, v35
	v_mul_f32_e32 v149, 0x3f4c422a, v149
	v_mul_f32_e32 v149, 0xc038aa3b, v149
	v_exp_f32_e32 v149, v149
	v_mul_f32_e32 v148, 0x3d372713, v38
	v_mul_f32_e32 v148, v38, v148
	v_fma_f32 v148, v38, v148, v38
	v_add_f32_e32 v149, 1.0, v149
	v_rcp_f32_e32 v172, v149
	v_mul_f32_e32 v149, 0x3d372713, v40
	v_mul_f32_e32 v149, v40, v149
	v_fma_f32 v149, v40, v149, v40
	v_mul_f32_e32 v149, 0x3f4c422a, v149
	v_mul_f32_e32 v149, 0xc038aa3b, v149
	v_exp_f32_e32 v149, v149
	v_mul_f32_e32 v148, 0x3f4c422a, v148
	v_mul_f32_e32 v168, 0x3d372713, v45
	v_mul_f32_e32 v148, 0xc038aa3b, v148
	v_add_f32_e32 v149, 1.0, v149
	v_rcp_f32_e32 v171, v149
	v_mul_f32_e32 v149, 0x3d372713, v36
	v_mul_f32_e32 v149, v36, v149
	v_fma_f32 v149, v36, v149, v36
	v_mul_f32_e32 v149, 0x3f4c422a, v149
	v_mul_f32_e32 v149, 0xc038aa3b, v149
	v_mul_f32_e32 v168, v45, v168
	v_exp_f32_e32 v148, v148
	v_exp_f32_e32 v149, v149
	v_fma_f32 v168, v45, v168, v45
	v_mul_f32_e32 v168, 0x3f4c422a, v168
	v_mul_f32_e32 v168, 0xc038aa3b, v168
	v_exp_f32_e32 v168, v168
	v_add_f32_e32 v148, 1.0, v148
	v_add_f32_e32 v149, 1.0, v149
	v_rcp_f32_e32 v169, v148
	v_mul_f32_e32 v148, 0x3d372713, v34
	v_rcp_f32_e32 v174, v149
	v_mul_f32_e32 v149, 0x3d372713, v41
	v_mul_f32_e32 v148, v34, v148
	v_mul_f32_e32 v149, v41, v149
	v_fma_f32 v148, v34, v148, v34
	v_fma_f32 v149, v41, v149, v41
	v_add_f32_e32 v168, 1.0, v168
	v_mul_f32_e32 v148, 0x3f4c422a, v148
	v_mul_f32_e32 v149, 0x3f4c422a, v149
	v_mul_f32_e32 v175, 0x3d372713, v37
	v_add_u32_e32 v144, 0x90, v142
	v_rcp_f32_e32 v168, v168
	v_mul_f32_e32 v148, 0xc038aa3b, v148
	v_mul_f32_e32 v149, 0xc038aa3b, v149
	v_mul_f32_e32 v175, v37, v175
	v_ashrrev_i32_e32 v145, 31, v144
	v_exp_f32_e32 v148, v148
	v_exp_f32_e32 v149, v149
	v_fma_f32 v175, v37, v175, v37
	v_lshlrev_b64 v[146:147], 12, v[144:145]
	v_mul_f32_e32 v175, 0x3f4c422a, v175
	v_lshl_add_u64 v[146:147], s[46:47], 0, v[146:147]
	v_mul_f32_e32 v175, 0xc038aa3b, v175
	v_pk_mov_b32 v[176:177], v[44:45], v[38:39] op_sel:[1,0]
	v_lshl_add_u64 v[146:147], v[146:147], 0, v[0:1]
	v_exp_f32_e32 v175, v175
	v_pk_mul_f32 v[168:169], v[176:177], v[168:169]
	v_add_f32_e32 v148, 1.0, v148
	v_add_f32_e32 v149, 1.0, v149
	v_add_f32_e32 v185, v168, v185
	v_pk_mul_f32 v[176:177], v[168:169], v[168:169]
	v_cvt_pk_bf16_f32 v167, v167, v168
	global_store_dwordx4 v[146:147], v[164:167], off
	v_rcp_f32_e32 v148, v148
	v_rcp_f32_e32 v149, v149
	v_mov_b32_e32 v164, v39
	v_mov_b32_e32 v165, v40
; __device__ __forceinline__ float gelu_f(float x) { const float u = 0.7978845608028654f * (x + 0.044715f * x * x * x); return x * frcp(1.f + fexp2(-2.885390081777927f * u)); }
; __device__ __forceinline__ void st8(bf16_t* p, const float (&v)[8]) { u32x4 w; w.x = pk2(v[0], v[1]); w.y = pk2(v[2], v[3]); w.z = pk2(v[4], v[5]); w.w = pk2(v[6], v[7]); *(u32x4*)p = w; }
;     __device__ __forceinline__ void operator()(const f32x4 (&acc)[2][2][4][2], const Unit& u, int wr, int wc, int fr, int fq) const {
;     ...
;                     for (int bj = 0; bj < 2; ++bj) { float o[8];
; #pragma unroll
;                         for (int j = 0; j < 4; ++j) { o[j] = gelu_f(acc[ai][bj][m][0][j]); o[4 + j] = gelu_f(acc[ai][bj][m][1][j]); }
; #pragma unroll
;                         for (int j = 0; j < 8; ++j) { s1 += o[j]; s2 += o[j] * o[j]; }
;                         st8(gv + (size_t)row * DM + colt + bj * 128, o); }
;                     s1 += __shfl_xor(s1, 16); s2 += __shfl_xor(s2, 16); s1 += __shfl_xor(s1, 32); s2 += __shfl_xor(s2, 32);
;                     if (fq == 0) { float2 w; w.x = s1; w.y = s2; *(float2*)(stats + ((size_t)row * 32 + (pn - 16) * 4 + wc) * 2) = w; }
	v_add_f32_e32 v176, v176, v186
	v_add_f32_e32 v166, v185, v169
	v_pk_mul_f32 v[164:165], v[164:165], v[170:171]
	v_add_f32_e32 v168, v176, v177
	v_add_f32_e32 v170, v164, v166
	v_pk_mul_f32 v[166:167], v[164:165], v[164:165]
	v_add_f32_e32 v175, 1.0, v175
	v_add_f32_e32 v166, v166, v168
	v_rcp_f32_e32 v175, v175
	v_add_f32_e32 v168, v165, v170
	v_add_f32_e32 v170, v167, v166
	v_mov_b32_e32 v166, v34
	v_mov_b32_e32 v167, v41
	v_pk_mul_f32 v[148:149], v[166:167], v[148:149]
	v_mul_f32_e32 v173, v35, v172
	v_pk_mul_f32 v[166:167], v[148:149], v[148:149]
	v_add_f32_e32 v168, v149, v168
	v_add_f32_e32 v167, v167, v170
	v_add_f32_e32 v168, v148, v168
	v_add_f32_e32 v167, v166, v167
	v_cvt_pk_bf16_f32 v165, v165, v149
	v_cvt_pk_bf16_f32 v166, v148, v173
	v_pk_mul_f32 v[148:149], v[36:37], v[174:175]
	v_fmac_f32_e32 v168, v35, v172
	v_mov_b32_e32 v172, v148
	v_cvt_pk_bf16_f32 v164, v169, v164
	v_pk_mul_f32 v[170:171], v[172:173], v[172:173]
	v_mov_b32_e32 v169, v149
	v_add_f32_e32 v167, v171, v167
	v_pk_fma_f32 v[168:169], v[36:37], v[174:175], v[168:169]
	v_pk_mul_f32 v[172:173], v[148:149], v[148:149]
	v_add_f32_e32 v171, v170, v167
	v_mov_b32_e32 v169, v173
	v_mov_b32_e32 v170, v149
	v_pk_add_f32 v[168:169], v[168:169], v[170:171]
	v_cvt_pk_bf16_f32 v167, v148, v149
	global_store_dwordx4 v[146:147], v[164:167], off offset:256
	ds_bpermute_b32 v146, v162, v168
	ds_bpermute_b32 v147, v162, v169
	s_waitcnt lgkmcnt(0)
	v_pk_add_f32 v[146:147], v[168:169], v[146:147]
	ds_bpermute_b32 v148, v163, v146
	ds_bpermute_b32 v149, v163, v147
	s_and_saveexec_b64 s[12:13], s[40:41]
	s_cbranch_execz .LBB0_325
	v_lshlrev_b64 v[144:145], 8, v[144:145]
	v_lshl_add_u64 v[144:145], s[48:49], 0, v[144:145]
	v_lshl_add_u64 v[144:145], s[30:31], 3, v[144:145]
	s_waitcnt lgkmcnt(0)
	v_pk_add_f32 v[146:147], v[146:147], v[148:149]
	global_store_dwordx2 v[144:145], v[146:147], off
.LBB0_325:
	s_or_b64 exec, exec, s[12:13]
	s_waitcnt lgkmcnt(0)
	v_mul_f32_e32 v149, 0x3d372713, v31
	v_mul_f32_e32 v149, v31, v149
	v_fma_f32 v149, v31, v149, v31
	v_mul_f32_e32 v149, 0x3f4c422a, v149
	v_mul_f32_e32 v149, 0xc038aa3b, v149
	v_exp_f32_e32 v149, v149
	v_mul_f32_e32 v148, 0x3d372713, v30
	v_mul_f32_e32 v148, v30, v148
	v_fma_f32 v148, v30, v148, v30
	v_add_f32_e32 v149, 1.0, v149
	v_rcp_f32_e32 v167, v149
	v_mul_f32_e32 v149, 0x3d372713, v27
	v_mul_f32_e32 v149, v27, v149
	v_fma_f32 v149, v27, v149, v27
	v_mul_f32_e32 v149, 0x3f4c422a, v149
	v_mul_f32_e32 v149, 0xc038aa3b, v149
	v_exp_f32_e32 v149, v149
	v_mul_f32_e32 v148, 0x3f4c422a, v148
	v_mul_f32_e32 v148, 0xc038aa3b, v148
	v_exp_f32_e32 v148, v148
	v_add_f32_e32 v149, 1.0, v149
	v_rcp_f32_e32 v164, v149
	v_mul_f32_e32 v149, 0x3d372713, v32
	v_mul_f32_e32 v149, v32, v149
	v_fma_f32 v149, v32, v149, v32
	v_mul_f32_e32 v149, 0x3f4c422a, v149
	v_mul_f32_e32 v149, 0xc038aa3b, v149
	v_exp_f32_e32 v149, v149
	v_add_f32_e32 v148, 1.0, v148
	v_rcp_f32_e32 v166, v148
	v_mul_f32_e32 v148, 0x3d372713, v26
	v_add_f32_e32 v149, 1.0, v149
	v_rcp_f32_e32 v171, v149
	v_mul_f32_e32 v149, 0x3d372713, v28
	v_mul_f32_e32 v149, v28, v149
	v_fma_f32 v149, v28, v149, v28
	v_mul_f32_e32 v149, 0x3f4c422a, v149
	v_mul_f32_e32 v149, 0xc038aa3b, v149
	v_exp_f32_e32 v149, v149
	v_mul_f32_e32 v148, v26, v148
	v_fma_f32 v148, v26, v148, v26
	v_mul_f32_e32 v148, 0x3f4c422a, v148
	v_add_f32_e32 v149, 1.0, v149
	v_rcp_f32_e32 v165, v149
	v_mul_f32_e32 v149, 0x3d372713, v33
	v_mul_f32_e32 v149, v33, v149
	v_fma_f32 v149, v33, v149, v33
	v_mul_f32_e32 v149, 0x3f4c422a, v149
	v_mul_f32_e32 v148, 0xc038aa3b, v148
	v_mul_f32_e32 v149, 0xc038aa3b, v149
	v_exp_f32_e32 v148, v148
	v_exp_f32_e32 v149, v149
	v_mul_f32_e32 v170, v31, v167
	v_fma_f32 v173, v30, v166, 0
	v_add_f32_e32 v148, 1.0, v148
	v_add_f32_e32 v149, 1.0, v149
	v_rcp_f32_e32 v148, v148
	v_rcp_f32_e32 v149, v149
	v_mul_f32_e32 v169, v30, v166
	v_fmac_f32_e32 v173, v31, v167
	v_mul_f32_e32 v174, v170, v170
	v_mov_b32_e32 v166, v26
	v_mov_b32_e32 v167, v33
	v_mul_f32_e32 v172, v32, v171
	v_fmac_f32_e32 v174, v169, v169
	v_pk_mul_f32 v[148:149], v[166:167], v[148:149]
	v_fmac_f32_e32 v174, v172, v172
	v_pk_mul_f32 v[166:167], v[148:149], v[148:149]
	v_fmac_f32_e32 v173, v32, v171
	v_add_f32_e32 v167, v167, v174
	v_add_f32_e32 v171, v149, v173
	v_add_f32_e32 v173, v166, v167
	v_mov_b32_e32 v166, v27
	v_mov_b32_e32 v167, v28
	v_pk_mul_f32 v[166:167], v[166:167], v[164:165]
	v_add_f32_e32 v171, v148, v171
	v_pk_mul_f32 v[164:165], v[166:167], v[166:167]
	v_add_f32_e32 v171, v166, v171
	v_add_f32_e32 v164, v164, v173
	v_add_f32_e32 v186, v165, v164
	v_cvt_pk_bf16_f32 v165, v172, v149
	v_mul_f32_e32 v149, 0x3d372713, v23
	v_mul_f32_e32 v149, v23, v149
	v_fma_f32 v149, v23, v149, v23
	v_mul_f32_e32 v149, 0x3f4c422a, v149
	v_mul_f32_e32 v149, 0xc038aa3b, v149
	v_exp_f32_e32 v149, v149
	v_cvt_pk_bf16_f32 v164, v169, v170
	v_add_f32_e32 v185, v167, v171
	v_cvt_pk_bf16_f32 v166, v148, v166
	v_add_f32_e32 v149, 1.0, v149
	v_rcp_f32_e32 v170, v149
	v_mul_f32_e32 v149, 0x3d372713, v19
	v_mul_f32_e32 v149, v19, v149
	v_fma_f32 v149, v19, v149, v19
	v_mul_f32_e32 v149, 0x3f4c422a, v149
	v_mul_f32_e32 v149, 0xc038aa3b, v149
	v_exp_f32_e32 v149, v149
	v_mul_f32_e32 v148, 0x3d372713, v22
	v_mul_f32_e32 v148, v22, v148
	v_fma_f32 v148, v22, v148, v22
	v_add_f32_e32 v149, 1.0, v149
	v_rcp_f32_e32 v172, v149
	v_mul_f32_e32 v149, 0x3d372713, v24
	v_mul_f32_e32 v149, v24, v149
	v_fma_f32 v149, v24, v149, v24
	v_mul_f32_e32 v149, 0x3f4c422a, v149
	v_mul_f32_e32 v149, 0xc038aa3b, v149
	v_exp_f32_e32 v149, v149
	v_mul_f32_e32 v148, 0x3f4c422a, v148
	v_mul_f32_e32 v168, 0x3d372713, v29
	v_mul_f32_e32 v148, 0xc038aa3b, v148
; __device__ __forceinline__ float gelu_f(float x) { const float u = 0.7978845608028654f * (x + 0.044715f * x * x * x); return x * frcp(1.f + fexp2(-2.885390081777927f * u)); }
; __device__ __forceinline__ void st8(bf16_t* p, const float (&v)[8]) { u32x4 w; w.x = pk2(v[0], v[1]); w.y = pk2(v[2], v[3]); w.z = pk2(v[4], v[5]); w.w = pk2(v[6], v[7]); *(u32x4*)p = w; }
;     __device__ __forceinline__ void operator()(const f32x4 (&acc)[2][2][4][2], const Unit& u, int wr, int wc, int fr, int fq) const {
;     ...
;                     for (int bj = 0; bj < 2; ++bj) { float o[8];
; #pragma unroll
;                         for (int j = 0; j < 4; ++j) { o[j] = gelu_f(acc[ai][bj][m][0][j]); o[4 + j] = gelu_f(acc[ai][bj][m][1][j]); }
; #pragma unroll
;                         for (int j = 0; j < 8; ++j) { s1 += o[j]; s2 += o[j] * o[j]; }
;                         st8(gv + (size_t)row * DM + colt + bj * 128, o); }
;                     s1 += __shfl_xor(s1, 16); s2 += __shfl_xor(s2, 16); s1 += __shfl_xor(s1, 32); s2 += __shfl_xor(s2, 32);
;                     if (fq == 0) { float2 w; w.x = s1; w.y = s2; *(float2*)(stats + ((size_t)row * 32 + (pn - 16) * 4 + wc) * 2) = w; }
	v_add_f32_e32 v149, 1.0, v149
	v_rcp_f32_e32 v171, v149
	v_mul_f32_e32 v149, 0x3d372713, v20
	v_mul_f32_e32 v149, v20, v149
	v_fma_f32 v149, v20, v149, v20
	v_mul_f32_e32 v149, 0x3f4c422a, v149
	v_mul_f32_e32 v149, 0xc038aa3b, v149
	v_mul_f32_e32 v168, v29, v168
	v_exp_f32_e32 v148, v148
	v_exp_f32_e32 v149, v149
	v_fma_f32 v168, v29, v168, v29
	v_mul_f32_e32 v168, 0x3f4c422a, v168
	v_mul_f32_e32 v168, 0xc038aa3b, v168
	v_exp_f32_e32 v168, v168
	v_add_f32_e32 v148, 1.0, v148
	v_add_f32_e32 v149, 1.0, v149
	v_rcp_f32_e32 v169, v148
	v_mul_f32_e32 v148, 0x3d372713, v18
	v_rcp_f32_e32 v174, v149
	v_mul_f32_e32 v149, 0x3d372713, v25
	v_mul_f32_e32 v148, v18, v148
	v_mul_f32_e32 v149, v25, v149
	v_fma_f32 v148, v18, v148, v18
	v_fma_f32 v149, v25, v149, v25
	v_add_f32_e32 v168, 1.0, v168
	v_mul_f32_e32 v148, 0x3f4c422a, v148
	v_mul_f32_e32 v149, 0x3f4c422a, v149
	v_mul_f32_e32 v175, 0x3d372713, v21
	v_add_u32_e32 v144, 0xa0, v142
	v_rcp_f32_e32 v168, v168
	v_mul_f32_e32 v148, 0xc038aa3b, v148
	v_mul_f32_e32 v149, 0xc038aa3b, v149
	v_mul_f32_e32 v175, v21, v175
	v_ashrrev_i32_e32 v145, 31, v144
	v_exp_f32_e32 v148, v148
	v_exp_f32_e32 v149, v149
	v_fma_f32 v175, v21, v175, v21
	v_lshlrev_b64 v[146:147], 12, v[144:145]
	v_mul_f32_e32 v175, 0x3f4c422a, v175
	v_lshl_add_u64 v[146:147], s[46:47], 0, v[146:147]
	v_mul_f32_e32 v175, 0xc038aa3b, v175
	v_pk_mov_b32 v[176:177], v[28:29], v[22:23] op_sel:[1,0]
	v_lshl_add_u64 v[146:147], v[146:147], 0, v[0:1]
	v_exp_f32_e32 v175, v175
	v_pk_mul_f32 v[168:169], v[176:177], v[168:169]
	v_add_f32_e32 v148, 1.0, v148
	v_add_f32_e32 v149, 1.0, v149
	v_add_f32_e32 v185, v168, v185
	v_pk_mul_f32 v[176:177], v[168:169], v[168:169]
	v_cvt_pk_bf16_f32 v167, v167, v168
	global_store_dwordx4 v[146:147], v[164:167], off
	v_rcp_f32_e32 v148, v148
	v_rcp_f32_e32 v149, v149
	v_mov_b32_e32 v164, v23
	v_mov_b32_e32 v165, v24
	v_add_f32_e32 v176, v176, v186
	v_add_f32_e32 v166, v185, v169
	v_pk_mul_f32 v[164:165], v[164:165], v[170:171]
	v_add_f32_e32 v168, v176, v177
	v_add_f32_e32 v170, v164, v166
	v_pk_mul_f32 v[166:167], v[164:165], v[164:165]
	v_add_f32_e32 v175, 1.0, v175
	v_add_f32_e32 v166, v166, v168
	v_rcp_f32_e32 v175, v175
	v_add_f32_e32 v168, v165, v170
	v_add_f32_e32 v170, v167, v166
	v_mov_b32_e32 v166, v18
	v_mov_b32_e32 v167, v25
	v_pk_mul_f32 v[148:149], v[166:167], v[148:149]
	v_mul_f32_e32 v173, v19, v172
	v_pk_mul_f32 v[166:167], v[148:149], v[148:149]
	v_add_f32_e32 v168, v149, v168
	v_add_f32_e32 v167, v167, v170
	v_add_f32_e32 v168, v148, v168
	v_add_f32_e32 v167, v166, v167
	v_cvt_pk_bf16_f32 v165, v165, v149
	v_cvt_pk_bf16_f32 v166, v148, v173
	v_pk_mul_f32 v[148:149], v[20:21], v[174:175]
	v_fmac_f32_e32 v168, v19, v172
	v_mov_b32_e32 v172, v148
	v_cvt_pk_bf16_f32 v164, v169, v164
	v_pk_mul_f32 v[170:171], v[172:173], v[172:173]
	v_mov_b32_e32 v169, v149
	v_add_f32_e32 v167, v171, v167
	v_pk_fma_f32 v[168:169], v[20:21], v[174:175], v[168:169]
	v_pk_mul_f32 v[172:173], v[148:149], v[148:149]
	v_add_f32_e32 v171, v170, v167
	v_mov_b32_e32 v169, v173
	v_mov_b32_e32 v170, v149
	v_pk_add_f32 v[168:169], v[168:169], v[170:171]
	v_cvt_pk_bf16_f32 v167, v148, v149
	global_store_dwordx4 v[146:147], v[164:167], off offset:256
	ds_bpermute_b32 v146, v162, v168
	ds_bpermute_b32 v147, v162, v169
	s_waitcnt lgkmcnt(0)
	v_pk_add_f32 v[146:147], v[168:169], v[146:147]
	ds_bpermute_b32 v148, v163, v146
	ds_bpermute_b32 v149, v163, v147
	s_and_saveexec_b64 s[12:13], s[40:41]
	s_cbranch_execz .LBB0_327
	v_lshlrev_b64 v[144:145], 8, v[144:145]
	v_lshl_add_u64 v[144:145], s[48:49], 0, v[144:145]
	v_lshl_add_u64 v[144:145], s[30:31], 3, v[144:145]
	s_waitcnt lgkmcnt(0)
	v_pk_add_f32 v[146:147], v[146:147], v[148:149]
	global_store_dwordx2 v[144:145], v[146:147], off
.LBB0_327:
	s_or_b64 exec, exec, s[12:13]
	s_waitcnt lgkmcnt(0)
	v_mul_f32_e32 v149, 0x3d372713, v15
	v_mul_f32_e32 v149, v15, v149
	v_fma_f32 v149, v15, v149, v15
	v_mul_f32_e32 v149, 0x3f4c422a, v149
	v_mul_f32_e32 v149, 0xc038aa3b, v149
	v_exp_f32_e32 v149, v149
	v_mul_f32_e32 v148, 0x3d372713, v14
	v_mul_f32_e32 v148, v14, v148
	v_fma_f32 v148, v14, v148, v14
	v_add_f32_e32 v149, 1.0, v149
	v_rcp_f32_e32 v167, v149
	v_mul_f32_e32 v149, 0x3d372713, v11
	v_mul_f32_e32 v149, v11, v149
	v_fma_f32 v149, v11, v149, v11
	v_mul_f32_e32 v149, 0x3f4c422a, v149
	v_mul_f32_e32 v149, 0xc038aa3b, v149
	v_exp_f32_e32 v149, v149
	v_mul_f32_e32 v148, 0x3f4c422a, v148
	v_mul_f32_e32 v148, 0xc038aa3b, v148
	v_exp_f32_e32 v148, v148
	v_add_f32_e32 v149, 1.0, v149
	v_rcp_f32_e32 v164, v149
	v_mul_f32_e32 v149, 0x3d372713, v16
	v_mul_f32_e32 v149, v16, v149
	v_fma_f32 v149, v16, v149, v16
	v_mul_f32_e32 v149, 0x3f4c422a, v149
	v_mul_f32_e32 v149, 0xc038aa3b, v149
	v_exp_f32_e32 v149, v149
	v_add_f32_e32 v148, 1.0, v148
	v_rcp_f32_e32 v166, v148
	v_mul_f32_e32 v148, 0x3d372713, v10
	v_add_f32_e32 v149, 1.0, v149
	v_rcp_f32_e32 v171, v149
	v_mul_f32_e32 v149, 0x3d372713, v12
	v_mul_f32_e32 v149, v12, v149
	v_fma_f32 v149, v12, v149, v12
	v_mul_f32_e32 v149, 0x3f4c422a, v149
	v_mul_f32_e32 v149, 0xc038aa3b, v149
	v_exp_f32_e32 v149, v149
	v_mul_f32_e32 v148, v10, v148
	v_fma_f32 v148, v10, v148, v10
	v_mul_f32_e32 v148, 0x3f4c422a, v148
	v_add_f32_e32 v149, 1.0, v149
	v_rcp_f32_e32 v165, v149
	v_mul_f32_e32 v149, 0x3d372713, v17
	v_mul_f32_e32 v149, v17, v149
	v_fma_f32 v149, v17, v149, v17
	v_mul_f32_e32 v149, 0x3f4c422a, v149
	v_mul_f32_e32 v148, 0xc038aa3b, v148
	v_mul_f32_e32 v149, 0xc038aa3b, v149
	v_exp_f32_e32 v148, v148
	v_exp_f32_e32 v149, v149
	v_add_u32_e32 v144, 0xb0, v142
; __device__ __forceinline__ float gelu_f(float x) { const float u = 0.7978845608028654f * (x + 0.044715f * x * x * x); return x * frcp(1.f + fexp2(-2.885390081777927f * u)); }
; __device__ __forceinline__ void st8(bf16_t* p, const float (&v)[8]) { u32x4 w; w.x = pk2(v[0], v[1]); w.y = pk2(v[2], v[3]); w.z = pk2(v[4], v[5]); w.w = pk2(v[6], v[7]); *(u32x4*)p = w; }
;     __device__ __forceinline__ void operator()(const f32x4 (&acc)[2][2][4][2], const Unit& u, int wr, int wc, int fr, int fq) const {
;     ...
;                     for (int bj = 0; bj < 2; ++bj) { float o[8];
; #pragma unroll
;                         for (int j = 0; j < 4; ++j) { o[j] = gelu_f(acc[ai][bj][m][0][j]); o[4 + j] = gelu_f(acc[ai][bj][m][1][j]); }
; #pragma unroll
;                         for (int j = 0; j < 8; ++j) { s1 += o[j]; s2 += o[j] * o[j]; }
;                         st8(gv + (size_t)row * DM + colt + bj * 128, o); }
;                     s1 += __shfl_xor(s1, 16); s2 += __shfl_xor(s2, 16); s1 += __shfl_xor(s1, 32); s2 += __shfl_xor(s2, 32);
;                     if (fq == 0) { float2 w; w.x = s1; w.y = s2; *(float2*)(stats + ((size_t)row * 32 + (pn - 16) * 4 + wc) * 2) = w; }
	v_ashrrev_i32_e32 v145, 31, v144
	v_add_f32_e32 v148, 1.0, v148
	v_add_f32_e32 v149, 1.0, v149
	v_rcp_f32_e32 v148, v148
	v_rcp_f32_e32 v149, v149
	v_lshlrev_b64 v[146:147], 12, v[144:145]
	v_mul_f32_e32 v170, v15, v167
	v_fma_f32 v173, v14, v166, 0
	v_mul_f32_e32 v169, v14, v166
	v_fmac_f32_e32 v173, v15, v167
	v_mul_f32_e32 v174, v170, v170
	v_mov_b32_e32 v166, v10
	v_mov_b32_e32 v167, v17
	v_lshl_add_u64 v[146:147], s[46:47], 0, v[146:147]
	v_mul_f32_e32 v172, v16, v171
	v_fmac_f32_e32 v174, v169, v169
	v_pk_mul_f32 v[148:149], v[166:167], v[148:149]
	v_lshl_add_u64 v[146:147], v[146:147], 0, v[0:1]
	v_mul_f32_e32 v0, 0x3d372713, v6
	v_fmac_f32_e32 v174, v172, v172
	v_pk_mul_f32 v[166:167], v[148:149], v[148:149]
	v_mul_f32_e32 v0, v6, v0
	v_fmac_f32_e32 v173, v16, v171
	v_add_f32_e32 v167, v167, v174
	v_fma_f32 v0, v6, v0, v6
	v_add_f32_e32 v171, v149, v173
	v_add_f32_e32 v173, v166, v167
	v_mov_b32_e32 v166, v11
	v_mov_b32_e32 v167, v12
	v_mul_f32_e32 v0, 0x3f4c422a, v0
	v_pk_mul_f32 v[166:167], v[166:167], v[164:165]
	v_mul_f32_e32 v0, 0xc038aa3b, v0
	v_pk_mul_f32 v[164:165], v[166:167], v[166:167]
	v_exp_f32_e32 v0, v0
	v_add_f32_e32 v164, v164, v173
	v_add_f32_e32 v186, v165, v164
	v_cvt_pk_bf16_f32 v165, v172, v149
	v_mul_f32_e32 v149, 0x3d372713, v8
	v_mul_f32_e32 v149, v8, v149
	v_add_f32_e32 v0, 1.0, v0
	v_fma_f32 v149, v8, v149, v8
	v_cvt_pk_bf16_f32 v164, v169, v170
	v_rcp_f32_e32 v169, v0
	v_mul_f32_e32 v0, 0x3d372713, v2
	v_mul_f32_e32 v149, 0x3f4c422a, v149
	v_mul_f32_e32 v0, v2, v0
	v_mul_f32_e32 v149, 0xc038aa3b, v149
	v_fma_f32 v0, v2, v0, v2
	v_exp_f32_e32 v149, v149
	v_mul_f32_e32 v0, 0x3f4c422a, v0
	v_mul_f32_e32 v0, 0xc038aa3b, v0
	v_add_f32_e32 v171, v148, v171
	v_exp_f32_e32 v0, v0
	v_add_f32_e32 v171, v166, v171
	v_add_f32_e32 v149, 1.0, v149
	v_add_f32_e32 v185, v167, v171
	v_rcp_f32_e32 v171, v149
	v_mul_f32_e32 v149, 0x3d372713, v4
	v_mul_f32_e32 v149, v4, v149
	v_add_f32_e32 v0, 1.0, v0
	v_fma_f32 v149, v4, v149, v4
	v_cvt_pk_bf16_f32 v166, v148, v166
	v_rcp_f32_e32 v148, v0
	v_mul_f32_e32 v0, 0x3d372713, v7
	v_mul_f32_e32 v149, 0x3f4c422a, v149
	v_mul_f32_e32 v168, 0x3d372713, v13
	v_mul_f32_e32 v0, v7, v0
	v_mul_f32_e32 v149, 0xc038aa3b, v149
	v_mul_f32_e32 v168, v13, v168
	v_fma_f32 v0, v7, v0, v7
	v_exp_f32_e32 v149, v149
	v_fma_f32 v168, v13, v168, v13
	v_mul_f32_e32 v0, 0x3f4c422a, v0
	v_mul_f32_e32 v168, 0x3f4c422a, v168
	v_mul_f32_e32 v0, 0xc038aa3b, v0
	v_mul_f32_e32 v168, 0xc038aa3b, v168
	v_exp_f32_e32 v0, v0
	v_exp_f32_e32 v168, v168
	v_add_f32_e32 v149, 1.0, v149
	v_mul_f32_e32 v172, 0x3d372713, v5
	v_rcp_f32_e32 v174, v149
	v_mul_f32_e32 v149, 0x3d372713, v9
	v_mul_f32_e32 v172, v5, v172
	v_mul_f32_e32 v149, v9, v149
	v_fma_f32 v172, v5, v172, v5
	v_add_f32_e32 v0, 1.0, v0
	v_fma_f32 v149, v9, v149, v9
	v_mul_f32_e32 v172, 0x3f4c422a, v172
	v_add_f32_e32 v168, 1.0, v168
	v_rcp_f32_e32 v170, v0
	v_mul_f32_e32 v0, 0x3d372713, v3
	v_mul_f32_e32 v149, 0x3f4c422a, v149
	v_mul_f32_e32 v172, 0xc038aa3b, v172
	v_rcp_f32_e32 v168, v168
	v_mul_f32_e32 v0, v3, v0
	v_mul_f32_e32 v149, 0xc038aa3b, v149
	v_exp_f32_e32 v172, v172
	v_fma_f32 v0, v3, v0, v3
	v_exp_f32_e32 v149, v149
	v_mul_f32_e32 v0, 0x3f4c422a, v0
	v_mul_f32_e32 v0, 0xc038aa3b, v0
	v_pk_mov_b32 v[176:177], v[12:13], v[6:7] op_sel:[1,0]
	v_exp_f32_e32 v0, v0
	v_add_f32_e32 v172, 1.0, v172
	v_pk_mul_f32 v[168:169], v[176:177], v[168:169]
	v_add_f32_e32 v149, 1.0, v149
	v_rcp_f32_e32 v175, v172
	v_add_f32_e32 v172, v168, v185
	v_pk_mul_f32 v[176:177], v[168:169], v[168:169]
	v_cvt_pk_bf16_f32 v167, v167, v168
	global_store_dwordx4 v[146:147], v[164:167], off
	v_rcp_f32_e32 v149, v149
	v_add_f32_e32 v176, v176, v186
	v_mov_b32_e32 v164, v7
	v_mov_b32_e32 v165, v8
	v_add_f32_e32 v166, v172, v169
	v_pk_mul_f32 v[164:165], v[164:165], v[170:171]
	v_add_f32_e32 v168, v176, v177
	v_add_f32_e32 v170, v164, v166
	v_pk_mul_f32 v[166:167], v[164:165], v[164:165]
	v_add_f32_e32 v0, 1.0, v0
	v_add_f32_e32 v166, v166, v168
	v_rcp_f32_e32 v0, v0
	v_add_f32_e32 v168, v165, v170
	v_add_f32_e32 v170, v167, v166
	v_mov_b32_e32 v166, v2
	v_mov_b32_e32 v167, v9
	v_pk_mul_f32 v[148:149], v[166:167], v[148:149]
	v_mul_f32_e32 v173, v3, v0
	v_pk_mul_f32 v[166:167], v[148:149], v[148:149]
	v_add_f32_e32 v168, v149, v168
	v_add_f32_e32 v167, v167, v170
	v_add_f32_e32 v168, v148, v168
	v_add_f32_e32 v167, v166, v167
	v_cvt_pk_bf16_f32 v165, v165, v149
	v_cvt_pk_bf16_f32 v166, v148, v173
	v_pk_mul_f32 v[148:149], v[4:5], v[174:175]
	v_fmac_f32_e32 v168, v3, v0
	v_mov_b32_e32 v172, v148
	v_cvt_pk_bf16_f32 v164, v169, v164
	v_pk_mul_f32 v[170:171], v[172:173], v[172:173]
	v_mov_b32_e32 v169, v149
	v_add_f32_e32 v0, v171, v167
	v_pk_fma_f32 v[168:169], v[4:5], v[174:175], v[168:169]
	v_pk_mul_f32 v[172:173], v[148:149], v[148:149]
	v_add_f32_e32 v171, v170, v0
	v_mov_b32_e32 v169, v173
	v_mov_b32_e32 v170, v149
	v_pk_add_f32 v[168:169], v[168:169], v[170:171]
	v_cvt_pk_bf16_f32 v167, v148, v149
	global_store_dwordx4 v[146:147], v[164:167], off offset:256
	ds_bpermute_b32 v146, v162, v168
	ds_bpermute_b32 v147, v162, v169
	s_waitcnt lgkmcnt(0)
	v_pk_add_f32 v[146:147], v[168:169], v[146:147]
	ds_bpermute_b32 v148, v163, v146
	ds_bpermute_b32 v149, v163, v147
	s_and_saveexec_b64 s[12:13], s[40:41]
	s_cbranch_execz .LBB0_329
	v_lshlrev_b64 v[144:145], 8, v[144:145]
	v_lshl_add_u64 v[144:145], s[48:49], 0, v[144:145]
	v_lshl_add_u64 v[144:145], s[30:31], 3, v[144:145]
	s_waitcnt lgkmcnt(0)
	v_pk_add_f32 v[146:147], v[146:147], v[148:149]
	global_store_dwordx2 v[144:145], v[146:147], off
